# differential-attention epilogues (context + latent): row-per-lane dwordx2 stores paired with v_permlane32_swap into dwordx4 stores (16 -> 8 per wave), ring vmcnt recounted
# speedup vs baseline: 1.0076x; 1.0076x over previous
.LBB0_854:
	s_cmpk_gt_u32 s10, 0xff
	s_waitcnt lgkmcnt(0)
	s_barrier
	s_barrier
	s_cbranch_scc1 .LBB0_829
	s_lshl_b32 s3, s10, 8
	v_lshl_add_u32 v68, v64, 2, 0
	s_and_b32 s4, s3, 0xc000
	v_add_u32_e32 v69, s4, v68
	ds_read2st64_b32 v[96:97], v69 offset1:1
	ds_read2st64_b32 v[98:99], v69 offset0:2 offset1:3
	ds_read2st64_b32 v[104:105], v69 offset0:4 offset1:5
	ds_read2st64_b32 v[108:109], v69 offset0:6 offset1:7
	ds_read2st64_b32 v[112:113], v69 offset0:8 offset1:9
	ds_read2st64_b32 v[114:115], v69 offset0:10 offset1:11
	ds_read2st64_b32 v[120:121], v69 offset0:12 offset1:13
	ds_read2st64_b32 v[124:125], v69 offset0:14 offset1:15
	ds_read2st64_b32 v[126:127], v69 offset0:16 offset1:17
	ds_read2st64_b32 v[122:123], v69 offset0:18 offset1:19
	ds_read2st64_b32 v[128:129], v69 offset0:20 offset1:21
	ds_read2st64_b32 v[134:135], v69 offset0:22 offset1:23
	ds_read2st64_b32 v[130:131], v69 offset0:24 offset1:25
	ds_read2st64_b32 v[138:139], v69 offset0:26 offset1:27
	ds_read2st64_b32 v[142:143], v69 offset0:28 offset1:29
	ds_read2st64_b32 v[166:167], v69 offset0:30 offset1:31
	ds_read2st64_b32 v[136:137], v69 offset0:32 offset1:33
	ds_read2st64_b32 v[148:149], v69 offset0:34 offset1:35
	ds_read2st64_b32 v[150:151], v69 offset0:36 offset1:37
	ds_read2st64_b32 v[152:153], v69 offset0:38 offset1:39
	ds_read2st64_b32 v[102:103], v69 offset0:40 offset1:41
	ds_read2st64_b32 v[106:107], v69 offset0:42 offset1:43
	ds_read2st64_b32 v[90:91], v69 offset0:44 offset1:45
	ds_read2st64_b32 v[92:93], v69 offset0:46 offset1:47
	ds_read2st64_b32 v[86:87], v69 offset0:48 offset1:49
	ds_read2st64_b32 v[88:89], v69 offset0:50 offset1:51
	ds_read2st64_b32 v[82:83], v69 offset0:52 offset1:53
	ds_read2st64_b32 v[84:85], v69 offset0:54 offset1:55
	ds_read2st64_b32 v[78:79], v69 offset0:56 offset1:57
	ds_read2st64_b32 v[80:81], v69 offset0:58 offset1:59
	ds_read2st64_b32 v[64:65], v69 offset0:60 offset1:61
	s_or_b32 s3, s3, 0x3f00
	s_lshl_b32 s2, s17, 7
	s_movk_i32 s4, 0x1400
	s_lshl_b32 s40, s2, 1
	s_waitcnt lgkmcnt(0)
	v_pk_mul_f32 v[64:65], v[144:145], v[64:65]
	v_pk_mul_f32 v[96:97], v[144:145], v[96:97]
	v_pk_fma_f32 v[66:67], v[12:13], v[72:73], v[64:65] op_sel_hi:[1,0,1] neg_lo:[0,0,1] neg_hi:[0,0,1]
	v_add_u32_e32 v13, s3, v68
	ds_read_b32 v12, v69 offset:15872
	ds_read_b32 v13, v13
	v_pk_mul_f32 v[98:99], v[144:145], v[98:99]
	v_pk_mul_f32 v[104:105], v[144:145], v[104:105]
	v_pk_mul_f32 v[108:109], v[144:145], v[108:109]
	v_pk_mul_f32 v[112:113], v[144:145], v[112:113]
	s_waitcnt lgkmcnt(0)
	v_pk_mul_f32 v[12:13], v[144:145], v[12:13]
	v_pk_mul_f32 v[114:115], v[144:145], v[114:115]
	v_pk_fma_f32 v[64:65], v[14:15], v[72:73], v[12:13] op_sel_hi:[1,0,1] neg_lo:[0,0,1] neg_hi:[0,0,1]
	v_mov_b64_e32 v[14:15], s[14:15]
	v_mad_u64_u32 v[14:15], s[2:3], v174, s4, v[14:15]
	v_mov_b32_e32 v68, v15
	v_mad_u64_u32 v[68:69], s[2:3], v173, s4, v[68:69]
	v_mov_b32_e32 v15, v68
	v_lshrrev_b32_e32 v68, 3, v172
	v_and_b32_e32 v73, 4, v68
	v_lshl_add_u64 v[12:13], v[146:147], 0, s[40:41]
	v_lshlrev_b32_e32 v192, 1, v73
	v_lshl_add_u64 v[12:13], v[12:13], 0, v[192:193]
	s_mov_b64 s[2:3], 0x1000
	v_lshl_add_u64 v[68:69], v[12:13], 0, s[2:3]
	v_add_co_u32_e32 v12, vcc, s5, v12
	v_pk_fma_f32 v[96:97], v[48:49], v[72:73], v[96:97] op_sel_hi:[1,0,1] neg_lo:[0,0,1] neg_hi:[0,0,1]
	s_nop 0
	v_addc_co_u32_e32 v13, vcc, 0, v13, vcc
	flat_load_dwordx2 v[100:101], v[12:13]
	flat_load_dwordx2 v[162:163], v[68:69] offset:16
	flat_load_dwordx2 v[140:141], v[68:69] offset:32
	flat_load_dwordx2 v[132:133], v[68:69] offset:48
	flat_load_dwordx2 v[180:181], v[68:69] offset:64
	flat_load_dwordx2 v[186:187], v[68:69] offset:80
	flat_load_dwordx2 v[184:185], v[68:69] offset:96
	flat_load_dwordx2 v[178:179], v[68:69] offset:112
	flat_load_dwordx2 v[146:147], v[68:69] offset:128
	flat_load_dwordx2 v[168:169], v[68:69] offset:144
	flat_load_dwordx2 v[160:161], v[68:69] offset:160
	flat_load_dwordx2 v[154:155], v[68:69] offset:176
	flat_load_dwordx2 v[118:119], v[68:69] offset:192
	flat_load_dwordx2 v[94:95], v[68:69] offset:208
	flat_load_dwordx2 v[70:71], v[68:69] offset:224
	s_nop 0
	flat_load_dwordx2 v[68:69], v[68:69] offset:240
	v_lshlrev_b32_e32 v205, 2, v73
	v_pk_fma_f32 v[50:51], v[50:51], v[72:73], v[98:99] op_sel_hi:[1,0,1] neg_lo:[0,0,1] neg_hi:[0,0,1]
	v_pk_mul_f32 v[120:121], v[144:145], v[120:121]
	v_pk_mul_f32 v[124:125], v[144:145], v[124:125]
	v_pk_mul_f32 v[122:123], v[144:145], v[122:123]
	v_pk_mul_f32 v[80:81], v[144:145], v[80:81]
	v_pk_mul_f32 v[78:79], v[144:145], v[78:79]
	v_pk_mul_f32 v[116:117], v[96:97], v[96:97]
	v_lshl_add_u64 v[156:157], v[14:15], 0, s[40:41]
	global_load_dwordx4 v[12:15], v205, s[0:1]
	global_load_dwordx4 v[240:243], v205, s[0:1] offset:32
	global_load_dwordx4 v[244:247], v205, s[0:1] offset:64
	global_load_dwordx4 v[248:251], v205, s[0:1] offset:96
	v_pk_mul_f32 v[110:111], v[50:51], v[50:51]
	v_pk_mul_f32 v[74:75], v[66:67], v[66:67]
	v_pk_mul_f32 v[76:77], v[64:65], v[64:65]
	s_mov_b32 s2, 0x800000
	s_waitcnt vmcnt(0) lgkmcnt(0)
	v_lshlrev_b32_e32 v48, 16, v100
	v_mul_f32_e32 v73, 0xbfb8aa3b, v48
	v_exp_f32_e32 v73, v73
	v_and_b32_e32 v49, 0xffff0000, v100
	v_add_f32_e32 v73, 1.0, v73
	v_rcp_f32_e32 v98, v73
	v_mul_f32_e32 v73, 0xbfb8aa3b, v49
	v_exp_f32_e32 v73, v73
	s_nop 0
	v_add_f32_e32 v73, 1.0, v73
	v_rcp_f32_e32 v99, v73
	s_nop 0
	v_pk_mul_f32 v[98:99], v[98:99], v[48:49]
	v_lshlrev_b32_e32 v48, 16, v101
	v_mul_f32_e32 v73, 0xbfb8aa3b, v48
	v_exp_f32_e32 v73, v73
	v_and_b32_e32 v49, 0xffff0000, v101
	v_add_f32_e32 v73, 1.0, v73
	v_rcp_f32_e32 v100, v73
	v_mul_f32_e32 v73, 0xbfb8aa3b, v49
	v_exp_f32_e32 v73, v73
	s_nop 0
	v_add_f32_e32 v73, 1.0, v73
	v_pk_fma_f32 v[52:53], v[52:53], v[72:73], v[104:105] op_sel_hi:[1,0,1] neg_lo:[0,0,1] neg_hi:[0,0,1]
	v_lshlrev_b32_e32 v104, 16, v162
	v_rcp_f32_e32 v101, v73
	v_pk_fma_f32 v[54:55], v[54:55], v[72:73], v[108:109] op_sel_hi:[1,0,1] neg_lo:[0,0,1] neg_hi:[0,0,1]
	v_mul_f32_e32 v73, 0xbfb8aa3b, v104
	v_exp_f32_e32 v73, v73
	v_and_b32_e32 v105, 0xffff0000, v162
	v_pk_mul_f32 v[158:159], v[52:53], v[52:53]
	v_pk_mul_f32 v[100:101], v[100:101], v[48:49]
	v_add_f32_e32 v73, 1.0, v73
	v_rcp_f32_e32 v108, v73
	v_mul_f32_e32 v73, 0xbfb8aa3b, v105
	v_exp_f32_e32 v73, v73
	v_lshl_add_u64 v[48:49], v[156:157], 0, v[192:193]
	v_pk_mul_f32 v[156:157], v[54:55], v[54:55]
	v_add_f32_e32 v73, 1.0, v73
	v_rcp_f32_e32 v109, v73
	s_nop 0
	v_pk_mul_f32 v[104:105], v[108:109], v[104:105]
	v_lshlrev_b32_e32 v108, 16, v163
	v_mul_f32_e32 v73, 0xbfb8aa3b, v108
	v_exp_f32_e32 v73, v73
	v_and_b32_e32 v109, 0xffff0000, v163
	v_add_f32_e32 v73, 1.0, v73
	v_rcp_f32_e32 v162, v73
	v_mul_f32_e32 v73, 0xbfb8aa3b, v109
	v_exp_f32_e32 v73, v73
	s_nop 0
	v_add_f32_e32 v73, 1.0, v73
	v_pk_fma_f32 v[56:57], v[56:57], v[72:73], v[112:113] op_sel_hi:[1,0,1] neg_lo:[0,0,1] neg_hi:[0,0,1]
	v_lshlrev_b32_e32 v112, 16, v140
	v_rcp_f32_e32 v163, v73
	v_pk_fma_f32 v[58:59], v[58:59], v[72:73], v[114:115] op_sel_hi:[1,0,1] neg_lo:[0,0,1] neg_hi:[0,0,1]
	v_mul_f32_e32 v73, 0xbfb8aa3b, v112
	v_exp_f32_e32 v73, v73
	v_and_b32_e32 v113, 0xffff0000, v140
	v_pk_mul_f32 v[164:165], v[56:57], v[56:57]
	v_pk_mul_f32 v[108:109], v[162:163], v[108:109]
	v_add_f32_e32 v73, 1.0, v73
	v_rcp_f32_e32 v114, v73
	v_mul_f32_e32 v73, 0xbfb8aa3b, v113
	v_exp_f32_e32 v73, v73
	v_pk_mul_f32 v[162:163], v[58:59], v[58:59]
	v_add_f32_e32 v73, 1.0, v73
	v_rcp_f32_e32 v115, v73
	s_nop 0
	v_pk_mul_f32 v[112:113], v[114:115], v[112:113]
	v_lshlrev_b32_e32 v114, 16, v141
	v_mul_f32_e32 v73, 0xbfb8aa3b, v114
	v_exp_f32_e32 v73, v73
	v_and_b32_e32 v115, 0xffff0000, v141
	v_add_f32_e32 v73, 1.0, v73
	v_rcp_f32_e32 v140, v73
	v_mul_f32_e32 v73, 0xbfb8aa3b, v115
	v_exp_f32_e32 v73, v73
	s_nop 0
	v_add_f32_e32 v73, 1.0, v73
	v_pk_fma_f32 v[60:61], v[60:61], v[72:73], v[120:121] op_sel_hi:[1,0,1] neg_lo:[0,0,1] neg_hi:[0,0,1]
	v_lshlrev_b32_e32 v120, 16, v132
	v_rcp_f32_e32 v141, v73
	v_pk_fma_f32 v[62:63], v[62:63], v[72:73], v[124:125] op_sel_hi:[1,0,1] neg_lo:[0,0,1] neg_hi:[0,0,1]
	v_mul_f32_e32 v73, 0xbfb8aa3b, v120
	v_exp_f32_e32 v73, v73
	v_and_b32_e32 v121, 0xffff0000, v132
	v_pk_mul_f32 v[114:115], v[140:141], v[114:115]
	v_pk_mul_f32 v[172:173], v[60:61], v[60:61]
	v_add_f32_e32 v73, 1.0, v73
	v_rcp_f32_e32 v124, v73
	v_mul_f32_e32 v73, 0xbfb8aa3b, v121
	v_exp_f32_e32 v73, v73
	v_pk_mul_f32 v[170:171], v[62:63], v[62:63]
	v_add_f32_e32 v73, 1.0, v73
	v_rcp_f32_e32 v125, v73
	s_nop 0
	v_pk_mul_f32 v[120:121], v[124:125], v[120:121]
	v_lshlrev_b32_e32 v124, 16, v133
	v_mul_f32_e32 v73, 0xbfb8aa3b, v124
	v_exp_f32_e32 v73, v73
	v_and_b32_e32 v125, 0xffff0000, v133
	v_add_f32_e32 v73, 1.0, v73
	v_rcp_f32_e32 v132, v73
	v_mul_f32_e32 v73, 0xbfb8aa3b, v125
	v_exp_f32_e32 v73, v73
	s_nop 0
	v_add_f32_e32 v73, 1.0, v73
	v_rcp_f32_e32 v133, v73
	v_pk_fma_f32 v[122:123], v[34:35], v[72:73], v[122:123] op_sel_hi:[1,0,1] neg_lo:[0,0,1] neg_hi:[0,0,1]
	v_pk_mul_f32 v[34:35], v[144:145], v[126:127]
	v_pk_mul_f32 v[174:175], v[122:123], v[122:123]
	v_pk_mul_f32 v[124:125], v[132:133], v[124:125]
	v_pk_fma_f32 v[132:133], v[32:33], v[72:73], v[34:35] op_sel_hi:[1,0,1] neg_lo:[0,0,1] neg_hi:[0,0,1]
	v_lshlrev_b32_e32 v32, 16, v180
	v_and_b32_e32 v33, 0xffff0000, v180
	v_mul_f32_e32 v34, 0xbfb8aa3b, v32
	v_mul_f32_e32 v35, 0xbfb8aa3b, v33
	v_exp_f32_e32 v34, v34
	v_exp_f32_e32 v35, v35
	v_pk_mul_f32 v[176:177], v[132:133], v[132:133]
	v_add_f32_e32 v34, 1.0, v34
	v_add_f32_e32 v35, 1.0, v35
	v_rcp_f32_e32 v34, v34
	v_rcp_f32_e32 v35, v35
	s_nop 0
	v_pk_mul_f32 v[140:141], v[34:35], v[32:33]
	v_lshlrev_b32_e32 v32, 16, v181
	v_and_b32_e32 v33, 0xffff0000, v181
	v_mul_f32_e32 v34, 0xbfb8aa3b, v32
	v_mul_f32_e32 v35, 0xbfb8aa3b, v33
	v_exp_f32_e32 v34, v34
	v_exp_f32_e32 v35, v35
	v_add_f32_e32 v34, 1.0, v34
	v_add_f32_e32 v35, 1.0, v35
	v_rcp_f32_e32 v34, v34
	v_rcp_f32_e32 v35, v35
	s_nop 0
	v_pk_mul_f32 v[126:127], v[34:35], v[32:33]
	v_pk_mul_f32 v[34:35], v[144:145], v[128:129]
	v_pk_mul_f32 v[32:33], v[144:145], v[134:135]
	v_pk_fma_f32 v[128:129], v[36:37], v[72:73], v[34:35] op_sel_hi:[1,0,1] neg_lo:[0,0,1] neg_hi:[0,0,1]
	v_lshlrev_b32_e32 v34, 16, v186
	v_and_b32_e32 v35, 0xffff0000, v186
	v_mul_f32_e32 v36, 0xbfb8aa3b, v34
	v_mul_f32_e32 v37, 0xbfb8aa3b, v35
	v_exp_f32_e32 v36, v36
	v_exp_f32_e32 v37, v37
	v_pk_fma_f32 v[32:33], v[38:39], v[72:73], v[32:33] op_sel_hi:[1,0,1] neg_lo:[0,0,1] neg_hi:[0,0,1]
	v_pk_mul_f32 v[182:183], v[128:129], v[128:129]
	v_add_f32_e32 v36, 1.0, v36
	v_add_f32_e32 v37, 1.0, v37
	v_rcp_f32_e32 v36, v36
	v_rcp_f32_e32 v37, v37
	v_pk_mul_f32 v[180:181], v[32:33], v[32:33]
	v_pk_mul_f32 v[134:135], v[36:37], v[34:35]
	v_lshlrev_b32_e32 v34, 16, v187
	v_and_b32_e32 v35, 0xffff0000, v187
	v_mul_f32_e32 v36, 0xbfb8aa3b, v34
	v_mul_f32_e32 v37, 0xbfb8aa3b, v35
	v_exp_f32_e32 v36, v36
	v_exp_f32_e32 v37, v37
	v_add_f32_e32 v36, 1.0, v36
	v_add_f32_e32 v37, 1.0, v37
	v_rcp_f32_e32 v36, v36
	v_rcp_f32_e32 v37, v37
	s_nop 0
	v_pk_mul_f32 v[38:39], v[36:37], v[34:35]
	v_pk_mul_f32 v[36:37], v[144:145], v[130:131]
	v_pk_mul_f32 v[34:35], v[144:145], v[138:139]
	v_pk_fma_f32 v[130:131], v[40:41], v[72:73], v[36:37] op_sel_hi:[1,0,1] neg_lo:[0,0,1] neg_hi:[0,0,1]
	v_lshlrev_b32_e32 v36, 16, v184
	v_and_b32_e32 v37, 0xffff0000, v184
	v_mul_f32_e32 v40, 0xbfb8aa3b, v36
	v_mul_f32_e32 v41, 0xbfb8aa3b, v37
	v_exp_f32_e32 v40, v40
	v_exp_f32_e32 v41, v41
	v_pk_fma_f32 v[34:35], v[42:43], v[72:73], v[34:35] op_sel_hi:[1,0,1] neg_lo:[0,0,1] neg_hi:[0,0,1]
	v_pk_mul_f32 v[42:43], v[144:145], v[142:143]
	v_add_f32_e32 v40, 1.0, v40
	v_add_f32_e32 v41, 1.0, v41
	v_rcp_f32_e32 v40, v40
	v_rcp_f32_e32 v41, v41
	v_pk_mul_f32 v[188:189], v[130:131], v[130:131]
	v_pk_mul_f32 v[186:187], v[34:35], v[34:35]
	v_pk_mul_f32 v[138:139], v[40:41], v[36:37]
	v_lshlrev_b32_e32 v36, 16, v185
	v_and_b32_e32 v37, 0xffff0000, v185
	v_mul_f32_e32 v40, 0xbfb8aa3b, v36
	v_mul_f32_e32 v41, 0xbfb8aa3b, v37
	v_exp_f32_e32 v40, v40
	v_exp_f32_e32 v41, v41
	v_add_f32_e32 v40, 1.0, v40
	v_add_f32_e32 v41, 1.0, v41
	v_rcp_f32_e32 v40, v40
	v_rcp_f32_e32 v41, v41
	s_nop 0
	v_pk_mul_f32 v[40:41], v[40:41], v[36:37]
	v_pk_mul_f32 v[36:37], v[144:145], v[166:167]
	s_nop 0
	v_pk_fma_f32 v[36:37], v[46:47], v[72:73], v[36:37] op_sel_hi:[1,0,1] neg_lo:[0,0,1] neg_hi:[0,0,1]
	v_pk_fma_f32 v[46:47], v[44:45], v[72:73], v[42:43] op_sel_hi:[1,0,1] neg_lo:[0,0,1] neg_hi:[0,0,1]
	v_lshlrev_b32_e32 v42, 16, v178
	v_and_b32_e32 v43, 0xffff0000, v178
	v_mul_f32_e32 v44, 0xbfb8aa3b, v42
	v_mul_f32_e32 v45, 0xbfb8aa3b, v43
	v_exp_f32_e32 v44, v44
	v_exp_f32_e32 v45, v45
	v_pk_mul_f32 v[184:185], v[46:47], v[46:47]
	v_pk_mul_f32 v[166:167], v[36:37], v[36:37]
	v_add_f32_e32 v44, 1.0, v44
	v_add_f32_e32 v45, 1.0, v45
	v_rcp_f32_e32 v44, v44
	v_rcp_f32_e32 v45, v45
	s_nop 0
	v_pk_mul_f32 v[142:143], v[44:45], v[42:43]
	v_lshlrev_b32_e32 v42, 16, v179
	v_and_b32_e32 v43, 0xffff0000, v179
	v_mul_f32_e32 v44, 0xbfb8aa3b, v42
	v_mul_f32_e32 v45, 0xbfb8aa3b, v43
	v_exp_f32_e32 v44, v44
	v_exp_f32_e32 v45, v45
	v_add_f32_e32 v44, 1.0, v44
	v_add_f32_e32 v45, 1.0, v45
	v_rcp_f32_e32 v44, v44
	v_rcp_f32_e32 v45, v45
	s_nop 0
	v_pk_mul_f32 v[42:43], v[44:45], v[42:43]
	v_pk_mul_f32 v[44:45], v[144:145], v[148:149]
	s_nop 0
	v_pk_fma_f32 v[18:19], v[18:19], v[72:73], v[44:45] op_sel_hi:[1,0,1] neg_lo:[0,0,1] neg_hi:[0,0,1]
	v_pk_mul_f32 v[44:45], v[144:145], v[136:137]
	v_pk_mul_f32 v[178:179], v[18:19], v[18:19]
	v_pk_fma_f32 v[136:137], v[16:17], v[72:73], v[44:45] op_sel_hi:[1,0,1] neg_lo:[0,0,1] neg_hi:[0,0,1]
	v_lshlrev_b32_e32 v16, 16, v146
	v_and_b32_e32 v17, 0xffff0000, v146
	v_mul_f32_e32 v44, 0xbfb8aa3b, v16
	v_mul_f32_e32 v45, 0xbfb8aa3b, v17
	v_exp_f32_e32 v44, v44
	v_exp_f32_e32 v45, v45
	v_pk_mul_f32 v[190:191], v[136:137], v[136:137]
	v_add_f32_e32 v44, 1.0, v44
	v_add_f32_e32 v45, 1.0, v45
	v_rcp_f32_e32 v44, v44
	v_rcp_f32_e32 v45, v45
	s_nop 0
	v_pk_mul_f32 v[148:149], v[44:45], v[16:17]
	v_lshlrev_b32_e32 v16, 16, v147
	v_and_b32_e32 v17, 0xffff0000, v147
	v_mul_f32_e32 v44, 0xbfb8aa3b, v16
	v_mul_f32_e32 v45, 0xbfb8aa3b, v17
	v_exp_f32_e32 v44, v44
	v_exp_f32_e32 v45, v45
	v_add_f32_e32 v44, 1.0, v44
	v_add_f32_e32 v45, 1.0, v45
	v_rcp_f32_e32 v44, v44
	v_rcp_f32_e32 v45, v45
	s_nop 0
	v_pk_mul_f32 v[44:45], v[44:45], v[16:17]
	v_pk_mul_f32 v[16:17], v[144:145], v[152:153]
	s_nop 0
	v_pk_fma_f32 v[16:17], v[22:23], v[72:73], v[16:17] op_sel_hi:[1,0,1] neg_lo:[0,0,1] neg_hi:[0,0,1]
	v_pk_mul_f32 v[22:23], v[144:145], v[150:151]
	v_pk_mul_f32 v[152:153], v[16:17], v[16:17]
	v_pk_fma_f32 v[146:147], v[20:21], v[72:73], v[22:23] op_sel_hi:[1,0,1] neg_lo:[0,0,1] neg_hi:[0,0,1]
	v_lshlrev_b32_e32 v20, 16, v168
	v_and_b32_e32 v21, 0xffff0000, v168
	v_mul_f32_e32 v22, 0xbfb8aa3b, v20
	v_mul_f32_e32 v23, 0xbfb8aa3b, v21
	v_exp_f32_e32 v22, v22
	v_exp_f32_e32 v23, v23
	v_pk_mul_f32 v[194:195], v[146:147], v[146:147]
	v_add_f32_e32 v22, 1.0, v22
	v_add_f32_e32 v23, 1.0, v23
	v_rcp_f32_e32 v22, v22
	v_rcp_f32_e32 v23, v23
	s_nop 0
	v_pk_mul_f32 v[150:151], v[22:23], v[20:21]
	v_lshlrev_b32_e32 v20, 16, v169
	v_and_b32_e32 v21, 0xffff0000, v169
	v_mul_f32_e32 v22, 0xbfb8aa3b, v20
	v_mul_f32_e32 v23, 0xbfb8aa3b, v21
	v_exp_f32_e32 v22, v22
	v_exp_f32_e32 v23, v23
	v_add_f32_e32 v22, 1.0, v22
	v_add_f32_e32 v23, 1.0, v23
	v_rcp_f32_e32 v22, v22
	v_rcp_f32_e32 v23, v23
	s_nop 0
	v_pk_mul_f32 v[22:23], v[22:23], v[20:21]
	v_pk_mul_f32 v[20:21], v[144:145], v[106:107]
	s_nop 0
	v_pk_fma_f32 v[20:21], v[26:27], v[72:73], v[20:21] op_sel_hi:[1,0,1] neg_lo:[0,0,1] neg_hi:[0,0,1]
	v_pk_mul_f32 v[26:27], v[144:145], v[102:103]
	v_pk_mul_f32 v[168:169], v[20:21], v[20:21]
	v_pk_fma_f32 v[102:103], v[24:25], v[72:73], v[26:27] op_sel_hi:[1,0,1] neg_lo:[0,0,1] neg_hi:[0,0,1]
	v_lshlrev_b32_e32 v24, 16, v160
	v_and_b32_e32 v25, 0xffff0000, v160
	v_mul_f32_e32 v26, 0xbfb8aa3b, v24
	v_mul_f32_e32 v27, 0xbfb8aa3b, v25
	v_exp_f32_e32 v26, v26
	v_exp_f32_e32 v27, v27
	v_pk_mul_f32 v[196:197], v[102:103], v[102:103]
	v_add_f32_e32 v26, 1.0, v26
	v_add_f32_e32 v27, 1.0, v27
	v_rcp_f32_e32 v26, v26
	v_rcp_f32_e32 v27, v27
	s_nop 0
	v_pk_mul_f32 v[106:107], v[26:27], v[24:25]
	v_lshlrev_b32_e32 v24, 16, v161
	v_and_b32_e32 v25, 0xffff0000, v161
	v_mul_f32_e32 v26, 0xbfb8aa3b, v24
	v_mul_f32_e32 v27, 0xbfb8aa3b, v25
	v_exp_f32_e32 v26, v26
	v_exp_f32_e32 v27, v27
	v_add_f32_e32 v26, 1.0, v26
	v_add_f32_e32 v27, 1.0, v27
	v_rcp_f32_e32 v26, v26
	v_rcp_f32_e32 v27, v27
	s_nop 0
	v_pk_mul_f32 v[26:27], v[26:27], v[24:25]
	v_pk_mul_f32 v[24:25], v[144:145], v[92:93]
	s_nop 0
	v_pk_fma_f32 v[24:25], v[30:31], v[72:73], v[24:25] op_sel_hi:[1,0,1] neg_lo:[0,0,1] neg_hi:[0,0,1]
	v_pk_mul_f32 v[30:31], v[144:145], v[90:91]
	v_pk_mul_f32 v[160:161], v[24:25], v[24:25]
	v_pk_fma_f32 v[90:91], v[28:29], v[72:73], v[30:31] op_sel_hi:[1,0,1] neg_lo:[0,0,1] neg_hi:[0,0,1]
	v_lshlrev_b32_e32 v28, 16, v154
	v_and_b32_e32 v29, 0xffff0000, v154
	v_mul_f32_e32 v30, 0xbfb8aa3b, v28
	v_mul_f32_e32 v31, 0xbfb8aa3b, v29
	v_exp_f32_e32 v30, v30
	v_exp_f32_e32 v31, v31
	v_pk_mul_f32 v[198:199], v[90:91], v[90:91]
	v_add_f32_e32 v30, 1.0, v30
	v_add_f32_e32 v31, 1.0, v31
	v_rcp_f32_e32 v30, v30
	v_rcp_f32_e32 v31, v31
	s_nop 0
	v_pk_mul_f32 v[92:93], v[30:31], v[28:29]
	v_lshlrev_b32_e32 v28, 16, v155
	v_and_b32_e32 v29, 0xffff0000, v155
	v_mul_f32_e32 v30, 0xbfb8aa3b, v28
	v_mul_f32_e32 v31, 0xbfb8aa3b, v29
	v_exp_f32_e32 v30, v30
	v_exp_f32_e32 v31, v31
	v_add_f32_e32 v30, 1.0, v30
	v_add_f32_e32 v31, 1.0, v31
	v_rcp_f32_e32 v30, v30
	v_rcp_f32_e32 v31, v31
	s_nop 0
	v_pk_mul_f32 v[28:29], v[30:31], v[28:29]
	v_pk_mul_f32 v[30:31], v[144:145], v[88:89]
	s_nop 0
	v_pk_fma_f32 v[2:3], v[2:3], v[72:73], v[30:31] op_sel_hi:[1,0,1] neg_lo:[0,0,1] neg_hi:[0,0,1]
	v_pk_mul_f32 v[30:31], v[144:145], v[86:87]
	v_pk_mul_f32 v[154:155], v[2:3], v[2:3]
	v_pk_fma_f32 v[86:87], v[0:1], v[72:73], v[30:31] op_sel_hi:[1,0,1] neg_lo:[0,0,1] neg_hi:[0,0,1]
	v_lshlrev_b32_e32 v0, 16, v118
	v_and_b32_e32 v1, 0xffff0000, v118
	v_mul_f32_e32 v30, 0xbfb8aa3b, v0
	v_mul_f32_e32 v31, 0xbfb8aa3b, v1
	v_exp_f32_e32 v30, v30
	v_exp_f32_e32 v31, v31
	v_pk_mul_f32 v[200:201], v[86:87], v[86:87]
	v_add_f32_e32 v30, 1.0, v30
	v_add_f32_e32 v31, 1.0, v31
	v_rcp_f32_e32 v30, v30
	v_rcp_f32_e32 v31, v31
	s_nop 0
	v_pk_mul_f32 v[88:89], v[30:31], v[0:1]
	v_lshlrev_b32_e32 v0, 16, v119
	v_and_b32_e32 v1, 0xffff0000, v119
	v_mul_f32_e32 v30, 0xbfb8aa3b, v0
	v_mul_f32_e32 v31, 0xbfb8aa3b, v1
	v_exp_f32_e32 v30, v30
	v_exp_f32_e32 v31, v31
	v_add_f32_e32 v30, 1.0, v30
	v_add_f32_e32 v31, 1.0, v31
	v_rcp_f32_e32 v30, v30
	v_rcp_f32_e32 v31, v31
	s_nop 0
	v_pk_mul_f32 v[30:31], v[30:31], v[0:1]
	v_pk_mul_f32 v[0:1], v[144:145], v[84:85]
	s_nop 0
	v_pk_fma_f32 v[0:1], v[6:7], v[72:73], v[0:1] op_sel_hi:[1,0,1] neg_lo:[0,0,1] neg_hi:[0,0,1]
	v_pk_mul_f32 v[6:7], v[144:145], v[82:83]
	v_pk_mul_f32 v[84:85], v[0:1], v[0:1]
	v_pk_fma_f32 v[6:7], v[4:5], v[72:73], v[6:7] op_sel_hi:[1,0,1] neg_lo:[0,0,1] neg_hi:[0,0,1]
	v_lshlrev_b32_e32 v4, 16, v94
	v_mul_f32_e32 v73, 0xbfb8aa3b, v4
	v_exp_f32_e32 v73, v73
	v_and_b32_e32 v5, 0xffff0000, v94
	v_pk_mul_f32 v[118:119], v[6:7], v[6:7]
	v_add_f32_e32 v73, 1.0, v73
	v_rcp_f32_e32 v82, v73
	v_mul_f32_e32 v73, 0xbfb8aa3b, v5
	v_exp_f32_e32 v73, v73
	s_nop 0
	v_add_f32_e32 v73, 1.0, v73
	v_rcp_f32_e32 v83, v73
	s_nop 0
	v_pk_mul_f32 v[82:83], v[82:83], v[4:5]
	v_lshlrev_b32_e32 v4, 16, v95
	v_mul_f32_e32 v73, 0xbfb8aa3b, v4
	v_exp_f32_e32 v73, v73
	v_and_b32_e32 v5, 0xffff0000, v95
	v_add_f32_e32 v73, 1.0, v73
	v_rcp_f32_e32 v94, v73
	v_mul_f32_e32 v73, 0xbfb8aa3b, v5
	v_exp_f32_e32 v73, v73
	s_nop 0
	v_add_f32_e32 v73, 1.0, v73
	v_rcp_f32_e32 v95, v73
	v_pk_fma_f32 v[10:11], v[10:11], v[72:73], v[80:81] op_sel_hi:[1,0,1] neg_lo:[0,0,1] neg_hi:[0,0,1]
	v_pk_fma_f32 v[72:73], v[8:9], v[72:73], v[78:79] op_sel_hi:[1,0,1] neg_lo:[0,0,1] neg_hi:[0,0,1]
	v_lshlrev_b32_e32 v78, 16, v70
	v_and_b32_e32 v79, 0xffff0000, v70
	v_mul_f32_e32 v70, 0xbfb8aa3b, v78
	v_exp_f32_e32 v70, v70
	v_pk_mul_f32 v[4:5], v[94:95], v[4:5]
	v_pk_mul_f32 v[8:9], v[72:73], v[72:73]
	v_pk_mul_f32 v[80:81], v[10:11], v[10:11]
	v_add_f32_e32 v70, 1.0, v70
	v_rcp_f32_e32 v94, v70
	v_mul_f32_e32 v70, 0xbfb8aa3b, v79
	v_exp_f32_e32 v70, v70
	s_nop 0
	v_add_f32_e32 v70, 1.0, v70
	v_rcp_f32_e32 v95, v70
	v_add_f32_e32 v70, v116, v117
	v_add_f32_e32 v70, v70, v110
	v_add_f32_e32 v70, v70, v111
	v_add_f32_e32 v70, v70, v158
	v_add_f32_e32 v70, v70, v159
	v_add_f32_e32 v70, v70, v156
	v_add_f32_e32 v70, v70, v157
	v_add_f32_e32 v70, v70, v164
	v_add_f32_e32 v70, v70, v165
	v_add_f32_e32 v70, v70, v162
	v_add_f32_e32 v70, v70, v163
	v_add_f32_e32 v70, v70, v172
	v_add_f32_e32 v70, v70, v173
	v_add_f32_e32 v70, v70, v170
	v_add_f32_e32 v70, v70, v171
	v_add_f32_e32 v70, v70, v176
	v_add_f32_e32 v70, v70, v177
	v_add_f32_e32 v70, v70, v174
	v_add_f32_e32 v70, v70, v175
	v_add_f32_e32 v70, v70, v182
	v_add_f32_e32 v70, v70, v183
	v_add_f32_e32 v70, v70, v180
	v_add_f32_e32 v70, v70, v181
	v_add_f32_e32 v70, v70, v188
	v_add_f32_e32 v70, v70, v189
	v_add_f32_e32 v70, v70, v186
	v_add_f32_e32 v70, v70, v187
	v_add_f32_e32 v70, v70, v184
	v_add_f32_e32 v70, v70, v185
	v_add_f32_e32 v70, v70, v166
	v_add_f32_e32 v70, v70, v167
	v_add_f32_e32 v70, v70, v190
	v_add_f32_e32 v70, v70, v191
	v_add_f32_e32 v70, v70, v178
	v_add_f32_e32 v70, v70, v179
	v_add_f32_e32 v70, v70, v194
	v_add_f32_e32 v70, v70, v195
	v_add_f32_e32 v70, v70, v152
	v_add_f32_e32 v70, v70, v153
	v_add_f32_e32 v70, v70, v196
	v_add_f32_e32 v70, v70, v197
	v_add_f32_e32 v70, v70, v168
	v_add_f32_e32 v70, v70, v169
	v_add_f32_e32 v70, v70, v198
	v_add_f32_e32 v70, v70, v199
	v_add_f32_e32 v70, v70, v160
	v_add_f32_e32 v70, v70, v161
	v_add_f32_e32 v70, v70, v200
	v_add_f32_e32 v70, v70, v201
	v_add_f32_e32 v70, v70, v154
	v_add_f32_e32 v70, v70, v155
	v_add_f32_e32 v70, v70, v118
	v_add_f32_e32 v70, v70, v119
	v_add_f32_e32 v70, v70, v84
	v_add_f32_e32 v70, v70, v85
	v_add_f32_e32 v8, v70, v8
	v_add_f32_e32 v8, v8, v9
	v_add_f32_e32 v8, v8, v80
	v_add_f32_e32 v8, v8, v81
	v_add_f32_e32 v8, v8, v74
	v_add_f32_e32 v8, v8, v75
	v_add_f32_e32 v8, v8, v76
	v_add_f32_e32 v8, v8, v77
	ds_bpermute_b32 v9, v218, v8
	v_pk_mul_f32 v[78:79], v[94:95], v[78:79]
	s_waitcnt lgkmcnt(0)
	v_add_f32_e32 v8, v8, v9
	v_fmamk_f32 v8, v8, 0x3c000000, v207
	v_cmp_gt_f32_e32 vcc, s2, v8
	v_mul_f32_e32 v9, 0x4b800000, v8
	s_nop 0
	v_cndmask_b32_e32 v8, v8, v9, vcc
	v_rsq_f32_e32 v8, v8
	s_nop 0
	v_mul_f32_e32 v9, 0x45800000, v8
	v_cndmask_b32_e32 v8, v8, v9, vcc
	v_mul_f32_e32 v8, v204, v8
	v_pk_mul_f32 v[74:75], v[96:97], v[8:9] op_sel_hi:[1,0]
	v_pk_mul_f32 v[50:51], v[50:51], v[8:9] op_sel_hi:[1,0]
	v_pk_mul_f32 v[12:13], v[74:75], v[12:13]
	v_pk_mul_f32 v[14:15], v[50:51], v[14:15]
	v_pk_mul_f32 v[12:13], v[98:99], v[12:13]
	v_pk_mul_f32 v[14:15], v[100:101], v[14:15]
	v_cvt_pk_bf16_f32 v232, v12, v13
	v_cvt_pk_bf16_f32 v233, v14, v15
	global_load_dwordx4 v[252:255], v205, s[0:1] offset:128
	v_pk_mul_f32 v[50:51], v[52:53], v[8:9] op_sel_hi:[1,0]
	v_pk_mul_f32 v[32:33], v[32:33], v[8:9] op_sel_hi:[1,0]
	v_pk_mul_f32 v[18:19], v[18:19], v[8:9] op_sel_hi:[1,0]
	v_pk_mul_f32 v[16:17], v[16:17], v[8:9] op_sel_hi:[1,0]
	v_pk_mul_f32 v[2:3], v[2:3], v[8:9] op_sel_hi:[1,0]
	v_pk_mul_f32 v[0:1], v[0:1], v[8:9] op_sel_hi:[1,0]
	v_pk_mul_f32 v[10:11], v[10:11], v[8:9] op_sel_hi:[1,0]
	v_pk_mul_f32 v[12:13], v[50:51], v[240:241]
	v_pk_mul_f32 v[50:51], v[54:55], v[8:9] op_sel_hi:[1,0]
	v_pk_mul_f32 v[12:13], v[104:105], v[12:13]
	v_pk_mul_f32 v[14:15], v[50:51], v[242:243]
	v_cvt_pk_bf16_f32 v234, v12, v13
	v_pk_mul_f32 v[14:15], v[108:109], v[14:15]
	v_pk_mul_f32 v[50:51], v[56:57], v[8:9] op_sel_hi:[1,0]
	v_cvt_pk_bf16_f32 v235, v14, v15
	v_and_b32_e32 v236, 32, v209
	v_lshrrev_b32_e32 v236, 2, v236
	v_mov_b32_e32 v237, 0
	v_lshl_add_u64 v[236:237], v[48:49], 0, v[236:237]
	s_nop 1
	v_permlane32_swap_b32_e32 v232, v234
	v_permlane32_swap_b32_e32 v233, v235
	flat_store_dwordx4 v[236:237], v[232:235] offset:1024
	global_load_dwordx4 v[240:243], v205, s[0:1] offset:160
	v_pk_mul_f32 v[12:13], v[50:51], v[244:245]
	v_pk_mul_f32 v[50:51], v[58:59], v[8:9] op_sel_hi:[1,0]
	v_pk_mul_f32 v[12:13], v[112:113], v[12:13]
	v_pk_mul_f32 v[14:15], v[50:51], v[246:247]
	v_cvt_pk_bf16_f32 v232, v12, v13
	v_pk_mul_f32 v[14:15], v[114:115], v[14:15]
	v_pk_mul_f32 v[50:51], v[60:61], v[8:9] op_sel_hi:[1,0]
	v_cvt_pk_bf16_f32 v233, v14, v15
	global_load_dwordx4 v[244:247], v205, s[0:1] offset:192
	v_pk_mul_f32 v[12:13], v[50:51], v[248:249]
	v_pk_mul_f32 v[50:51], v[62:63], v[8:9] op_sel_hi:[1,0]
	v_pk_mul_f32 v[12:13], v[120:121], v[12:13]
	v_pk_mul_f32 v[14:15], v[50:51], v[250:251]
	v_cvt_pk_bf16_f32 v234, v12, v13
	v_pk_mul_f32 v[14:15], v[124:125], v[14:15]
	v_pk_mul_f32 v[50:51], v[132:133], v[8:9] op_sel_hi:[1,0]
	v_cvt_pk_bf16_f32 v235, v14, v15
	s_nop 1
	v_permlane32_swap_b32_e32 v232, v234
	v_permlane32_swap_b32_e32 v233, v235
	flat_store_dwordx4 v[236:237], v[232:235] offset:1056
	global_load_dwordx4 v[248:251], v205, s[0:1] offset:224
	s_waitcnt vmcnt(5)
	v_pk_mul_f32 v[12:13], v[50:51], v[252:253]
	v_pk_mul_f32 v[50:51], v[122:123], v[8:9] op_sel_hi:[1,0]
	v_pk_mul_f32 v[12:13], v[140:141], v[12:13]
	v_pk_mul_f32 v[14:15], v[50:51], v[254:255]
	v_cvt_pk_bf16_f32 v232, v12, v13
	v_pk_mul_f32 v[14:15], v[126:127], v[14:15]
	v_pk_mul_f32 v[50:51], v[128:129], v[8:9] op_sel_hi:[1,0]
	v_cvt_pk_bf16_f32 v233, v14, v15
	global_load_dwordx4 v[252:255], v205, s[0:1] offset:256
	s_waitcnt vmcnt(4)
	v_pk_mul_f32 v[12:13], v[50:51], v[240:241]
	v_pk_mul_f32 v[14:15], v[32:33], v[242:243]
	v_pk_mul_f32 v[12:13], v[134:135], v[12:13]
	v_pk_mul_f32 v[14:15], v[38:39], v[14:15]
	v_cvt_pk_bf16_f32 v234, v12, v13
	v_cvt_pk_bf16_f32 v235, v14, v15
	s_nop 1
	v_permlane32_swap_b32_e32 v232, v234
	v_permlane32_swap_b32_e32 v233, v235
	flat_store_dwordx4 v[236:237], v[232:235] offset:1088
	global_load_dwordx4 v[240:243], v205, s[0:1] offset:288
	v_pk_mul_f32 v[32:33], v[130:131], v[8:9] op_sel_hi:[1,0]
	s_waitcnt vmcnt(5)
	v_pk_mul_f32 v[12:13], v[32:33], v[244:245]
	v_pk_mul_f32 v[32:33], v[34:35], v[8:9] op_sel_hi:[1,0]
	v_pk_mul_f32 v[12:13], v[138:139], v[12:13]
	v_pk_mul_f32 v[14:15], v[32:33], v[246:247]
	v_cvt_pk_bf16_f32 v232, v12, v13
	v_pk_mul_f32 v[14:15], v[40:41], v[14:15]
	v_pk_mul_f32 v[32:33], v[46:47], v[8:9] op_sel_hi:[1,0]
	v_cvt_pk_bf16_f32 v233, v14, v15
	global_load_dwordx4 v[244:247], v205, s[0:1] offset:320
	s_waitcnt vmcnt(4)
	v_pk_mul_f32 v[12:13], v[32:33], v[248:249]
	v_pk_mul_f32 v[32:33], v[36:37], v[8:9] op_sel_hi:[1,0]
	v_pk_mul_f32 v[12:13], v[142:143], v[12:13]
	v_pk_mul_f32 v[14:15], v[32:33], v[250:251]
	v_cvt_pk_bf16_f32 v234, v12, v13
	v_pk_mul_f32 v[14:15], v[42:43], v[14:15]
	v_pk_mul_f32 v[32:33], v[136:137], v[8:9] op_sel_hi:[1,0]
	v_cvt_pk_bf16_f32 v235, v14, v15
	s_nop 1
	v_permlane32_swap_b32_e32 v232, v234
	v_permlane32_swap_b32_e32 v233, v235
	flat_store_dwordx4 v[236:237], v[232:235] offset:1120
	global_load_dwordx4 v[248:251], v205, s[0:1] offset:352
	s_waitcnt vmcnt(5)
	v_pk_mul_f32 v[12:13], v[32:33], v[252:253]
	v_pk_mul_f32 v[14:15], v[18:19], v[254:255]
	v_pk_mul_f32 v[12:13], v[148:149], v[12:13]
	v_pk_mul_f32 v[14:15], v[44:45], v[14:15]
	v_cvt_pk_bf16_f32 v232, v12, v13
	v_cvt_pk_bf16_f32 v233, v14, v15
	global_load_dwordx4 v[252:255], v205, s[0:1] offset:384
	v_pk_mul_f32 v[18:19], v[146:147], v[8:9] op_sel_hi:[1,0]
	s_waitcnt vmcnt(4)
	v_pk_mul_f32 v[14:15], v[16:17], v[242:243]
	v_pk_mul_f32 v[12:13], v[18:19], v[240:241]
	v_pk_mul_f32 v[14:15], v[22:23], v[14:15]
	v_pk_mul_f32 v[12:13], v[150:151], v[12:13]
	v_pk_mul_f32 v[16:17], v[102:103], v[8:9] op_sel_hi:[1,0]
	v_cvt_pk_bf16_f32 v234, v12, v13
	v_cvt_pk_bf16_f32 v235, v14, v15
	s_nop 1
	v_permlane32_swap_b32_e32 v232, v234
	v_permlane32_swap_b32_e32 v233, v235
	flat_store_dwordx4 v[236:237], v[232:235] offset:1152
	global_load_dwordx4 v[240:243], v205, s[0:1] offset:416
	s_waitcnt vmcnt(5)
	v_pk_mul_f32 v[12:13], v[16:17], v[244:245]
	v_pk_mul_f32 v[16:17], v[20:21], v[8:9] op_sel_hi:[1,0]
	v_pk_mul_f32 v[12:13], v[106:107], v[12:13]
	v_pk_mul_f32 v[14:15], v[16:17], v[246:247]
	v_cvt_pk_bf16_f32 v232, v12, v13
	v_pk_mul_f32 v[14:15], v[26:27], v[14:15]
	v_pk_mul_f32 v[16:17], v[90:91], v[8:9] op_sel_hi:[1,0]
	v_cvt_pk_bf16_f32 v233, v14, v15
	global_load_dwordx4 v[244:247], v205, s[0:1] offset:448
	s_waitcnt vmcnt(4)
	v_pk_mul_f32 v[12:13], v[16:17], v[248:249]
	v_pk_mul_f32 v[16:17], v[24:25], v[8:9] op_sel_hi:[1,0]
	v_pk_mul_f32 v[12:13], v[92:93], v[12:13]
	v_pk_mul_f32 v[14:15], v[16:17], v[250:251]
	v_cvt_pk_bf16_f32 v234, v12, v13
	v_pk_mul_f32 v[14:15], v[28:29], v[14:15]
	v_pk_mul_f32 v[16:17], v[86:87], v[8:9] op_sel_hi:[1,0]
	v_cvt_pk_bf16_f32 v235, v14, v15
	s_nop 1
	v_permlane32_swap_b32_e32 v232, v234
	v_permlane32_swap_b32_e32 v233, v235
	flat_store_dwordx4 v[236:237], v[232:235] offset:1184
	global_load_dwordx4 v[248:251], v205, s[0:1] offset:480
	s_waitcnt vmcnt(5)
	v_pk_mul_f32 v[12:13], v[16:17], v[252:253]
	v_pk_mul_f32 v[2:3], v[2:3], v[254:255]
	v_pk_mul_f32 v[12:13], v[88:89], v[12:13]
	v_pk_mul_f32 v[2:3], v[30:31], v[2:3]
	v_cvt_pk_bf16_f32 v232, v12, v13
	v_cvt_pk_bf16_f32 v233, v2, v3
	v_pk_mul_f32 v[2:3], v[6:7], v[8:9] op_sel_hi:[1,0]
	s_waitcnt vmcnt(3)
	v_pk_mul_f32 v[0:1], v[0:1], v[242:243]
	v_pk_mul_f32 v[2:3], v[2:3], v[240:241]
	v_pk_mul_f32 v[0:1], v[4:5], v[0:1]
	v_pk_mul_f32 v[2:3], v[82:83], v[2:3]
	v_pk_mul_f32 v[4:5], v[72:73], v[8:9] op_sel_hi:[1,0]
	v_cvt_pk_bf16_f32 v234, v2, v3
	v_cvt_pk_bf16_f32 v235, v0, v1
	s_nop 1
	v_permlane32_swap_b32_e32 v232, v234
	v_permlane32_swap_b32_e32 v233, v235
	flat_store_dwordx4 v[236:237], v[232:235] offset:1216
	s_waitcnt vmcnt(3)
	v_pk_mul_f32 v[0:1], v[4:5], v[244:245]
	s_nop 0
	v_pk_mul_f32 v[0:1], v[78:79], v[0:1]
	v_lshlrev_b32_e32 v4, 16, v71
	v_cvt_pk_bf16_f32 v232, v0, v1
	v_mul_f32_e32 v1, 0xbfb8aa3b, v4
	v_exp_f32_e32 v1, v1
	v_and_b32_e32 v5, 0xffff0000, v71
	v_pk_mul_f32 v[2:3], v[10:11], v[246:247]
	v_pk_mul_f32 v[10:11], v[66:67], v[8:9] op_sel_hi:[1,0]
	v_add_f32_e32 v1, 1.0, v1
	v_rcp_f32_e32 v6, v1
	v_mul_f32_e32 v1, 0xbfb8aa3b, v5
	v_exp_f32_e32 v1, v1
	v_pk_mul_f32 v[8:9], v[64:65], v[8:9] op_sel_hi:[1,0]
	v_add_f32_e32 v1, 1.0, v1
	v_rcp_f32_e32 v7, v1
	s_nop 0
	v_pk_mul_f32 v[4:5], v[6:7], v[4:5]
	s_nop 0
	v_pk_mul_f32 v[2:3], v[4:5], v[2:3]
	v_lshlrev_b32_e32 v4, 16, v68
	v_cvt_pk_bf16_f32 v233, v2, v3
	v_and_b32_e32 v5, 0xffff0000, v68
	v_mul_f32_e32 v6, 0xbfb8aa3b, v4
	v_mul_f32_e32 v7, 0xbfb8aa3b, v5
	v_exp_f32_e32 v6, v6
	v_exp_f32_e32 v7, v7
	v_add_f32_e32 v6, 1.0, v6
	v_add_f32_e32 v7, 1.0, v7
	v_rcp_f32_e32 v6, v6
	v_rcp_f32_e32 v7, v7
	s_waitcnt vmcnt(1)
	v_pk_mul_f32 v[0:1], v[10:11], v[248:249]
	v_pk_mul_f32 v[4:5], v[6:7], v[4:5]
	v_pk_mul_f32 v[2:3], v[8:9], v[250:251]
	v_pk_mul_f32 v[0:1], v[4:5], v[0:1]
	v_lshlrev_b32_e32 v4, 16, v69
	v_cvt_pk_bf16_f32 v234, v0, v1
	v_mul_f32_e32 v1, 0xbfb8aa3b, v4
	v_exp_f32_e32 v1, v1
	v_and_b32_e32 v5, 0xffff0000, v69
	v_add_f32_e32 v1, 1.0, v1
	v_rcp_f32_e32 v6, v1
	v_mul_f32_e32 v1, 0xbfb8aa3b, v5
	v_exp_f32_e32 v1, v1
	s_nop 0
	v_add_f32_e32 v1, 1.0, v1
	v_rcp_f32_e32 v7, v1
	s_nop 0
	v_pk_mul_f32 v[4:5], v[6:7], v[4:5]
	s_nop 0
	v_pk_mul_f32 v[2:3], v[4:5], v[2:3]
	s_nop 0
	v_cvt_pk_bf16_f32 v235, v2, v3
	s_nop 1
	v_permlane32_swap_b32_e32 v232, v234
	v_permlane32_swap_b32_e32 v233, v235
	flat_store_dwordx4 v[236:237], v[232:235] offset:1248
	s_branch .LBB0_829

.LBB0_956:
	s_cmpk_gt_u32 s37, 0xff
	s_waitcnt lgkmcnt(0)
	s_barrier
	s_cbranch_scc1 .LBB0_924
	s_lshl_b32 s0, s37, 8
	v_lshl_add_u32 v68, v64, 2, 0
	s_and_b32 s1, s0, 0xc000
	v_add_u32_e32 v69, s1, v68
	ds_read2st64_b32 v[96:97], v69 offset1:1
	ds_read2st64_b32 v[98:99], v69 offset0:2 offset1:3
	ds_read2st64_b32 v[112:113], v69 offset0:4 offset1:5
	ds_read2st64_b32 v[116:117], v69 offset0:6 offset1:7
	ds_read2st64_b32 v[118:119], v69 offset0:8 offset1:9
	ds_read2st64_b32 v[120:121], v69 offset0:10 offset1:11
	ds_read2st64_b32 v[122:123], v69 offset0:12 offset1:13
	ds_read2st64_b32 v[126:127], v69 offset0:14 offset1:15
	ds_read2st64_b32 v[128:129], v69 offset0:16 offset1:17
	ds_read2st64_b32 v[124:125], v69 offset0:18 offset1:19
	ds_read2st64_b32 v[130:131], v69 offset0:20 offset1:21
	ds_read2st64_b32 v[138:139], v69 offset0:22 offset1:23
	ds_read2st64_b32 v[132:133], v69 offset0:24 offset1:25
	ds_read2st64_b32 v[144:145], v69 offset0:26 offset1:27
	ds_read2st64_b32 v[148:149], v69 offset0:28 offset1:29
	ds_read2st64_b32 v[164:165], v69 offset0:30 offset1:31
	ds_read2st64_b32 v[140:141], v69 offset0:32 offset1:33
	ds_read2st64_b32 v[150:151], v69 offset0:34 offset1:35
	ds_read2st64_b32 v[134:135], v69 offset0:36 offset1:37
	ds_read2st64_b32 v[142:143], v69 offset0:38 offset1:39
	ds_read2st64_b32 v[104:105], v69 offset0:40 offset1:41
	ds_read2st64_b32 v[106:107], v69 offset0:42 offset1:43
	ds_read2st64_b32 v[90:91], v69 offset0:44 offset1:45
	ds_read2st64_b32 v[92:93], v69 offset0:46 offset1:47
	ds_read2st64_b32 v[86:87], v69 offset0:48 offset1:49
	ds_read2st64_b32 v[88:89], v69 offset0:50 offset1:51
	ds_read2st64_b32 v[82:83], v69 offset0:52 offset1:53
	ds_read2st64_b32 v[84:85], v69 offset0:54 offset1:55
	ds_read2st64_b32 v[78:79], v69 offset0:56 offset1:57
	ds_read2st64_b32 v[80:81], v69 offset0:58 offset1:59
	ds_read2st64_b32 v[64:65], v69 offset0:60 offset1:61
	s_or_b32 s0, s0, 0x3f00
	s_movk_i32 s6, 0x1400
	s_mov_b32 s3, s41
	s_waitcnt lgkmcnt(14)
	v_pk_mul_f32 v[96:97], v[160:161], v[96:97]
	s_waitcnt lgkmcnt(0)
	v_pk_mul_f32 v[64:65], v[160:161], v[64:65]
	v_pk_mul_f32 v[98:99], v[160:161], v[98:99]
	v_pk_fma_f32 v[66:67], v[12:13], v[72:73], v[64:65] op_sel_hi:[1,0,1] neg_lo:[0,0,1] neg_hi:[0,0,1]
	v_add_u32_e32 v13, s0, v68
	ds_read_b32 v12, v69 offset:15872
	ds_read_b32 v13, v13
	v_pk_mul_f32 v[112:113], v[160:161], v[112:113]
	v_pk_mul_f32 v[116:117], v[160:161], v[116:117]
	v_pk_mul_f32 v[118:119], v[160:161], v[118:119]
	v_pk_mul_f32 v[120:121], v[160:161], v[120:121]
	s_waitcnt lgkmcnt(0)
	v_pk_mul_f32 v[12:13], v[160:161], v[12:13]
	v_pk_mul_f32 v[122:123], v[160:161], v[122:123]
	v_pk_fma_f32 v[64:65], v[14:15], v[72:73], v[12:13] op_sel_hi:[1,0,1] neg_lo:[0,0,1] neg_hi:[0,0,1]
	v_mov_b64_e32 v[14:15], s[4:5]
	v_mad_u64_u32 v[14:15], s[0:1], v196, s6, v[14:15]
	v_mov_b32_e32 v68, v15
	v_mad_u64_u32 v[68:69], s[0:1], v195, s6, v[68:69]
	v_mov_b32_e32 v15, v68
	v_lshrrev_b32_e32 v68, 3, v194
	v_and_b32_e32 v73, 4, v68
	v_lshl_add_u64 v[12:13], v[162:163], 0, s[2:3]
	v_lshlrev_b32_e32 v192, 1, v73
	v_lshl_add_u64 v[12:13], v[12:13], 0, v[192:193]
	s_mov_b64 s[0:1], 0x1000
	v_lshl_add_u64 v[68:69], v[12:13], 0, s[0:1]
	s_movk_i32 s0, 0x1000
	v_add_co_u32_e32 v12, vcc, s0, v12
	v_pk_fma_f32 v[96:97], v[48:49], v[72:73], v[96:97] op_sel_hi:[1,0,1] neg_lo:[0,0,1] neg_hi:[0,0,1]
	s_nop 0
	v_addc_co_u32_e32 v13, vcc, 0, v13, vcc
	global_load_dwordx2 v[100:101], v[12:13], off
	global_load_dwordx2 v[162:163], v[68:69], off offset:16
	global_load_dwordx2 v[146:147], v[68:69], off offset:32
	global_load_dwordx2 v[136:137], v[68:69], off offset:48
	global_load_dwordx2 v[182:183], v[68:69], off offset:64
	global_load_dwordx2 v[188:189], v[68:69], off offset:80
	global_load_dwordx2 v[186:187], v[68:69], off offset:96
	global_load_dwordx2 v[180:181], v[68:69], off offset:112
	global_load_dwordx2 v[174:175], v[68:69], off offset:128
	global_load_dwordx2 v[168:169], v[68:69], off offset:144
	global_load_dwordx2 v[158:159], v[68:69], off offset:160
	global_load_dwordx2 v[152:153], v[68:69], off offset:176
	global_load_dwordx2 v[114:115], v[68:69], off offset:192
	global_load_dwordx2 v[94:95], v[68:69], off offset:208
	global_load_dwordx2 v[70:71], v[68:69], off offset:224
	s_nop 0
	global_load_dwordx2 v[68:69], v[68:69], off offset:240
	v_lshlrev_b32_e32 v205, 2, v73
	v_pk_fma_f32 v[50:51], v[50:51], v[72:73], v[98:99] op_sel_hi:[1,0,1] neg_lo:[0,0,1] neg_hi:[0,0,1]
	v_pk_mul_f32 v[126:127], v[160:161], v[126:127]
	v_pk_mul_f32 v[124:125], v[160:161], v[124:125]
	v_pk_mul_f32 v[80:81], v[160:161], v[80:81]
	v_pk_mul_f32 v[78:79], v[160:161], v[78:79]
	v_pk_mul_f32 v[110:111], v[96:97], v[96:97]
	v_lshl_add_u64 v[154:155], v[14:15], 0, s[2:3]
	global_load_dwordx4 v[12:15], v205, s[10:11]
	global_load_dwordx4 v[240:243], v205, s[10:11] offset:32
	global_load_dwordx4 v[244:247], v205, s[10:11] offset:64
	global_load_dwordx4 v[248:251], v205, s[10:11] offset:96
	v_pk_mul_f32 v[108:109], v[50:51], v[50:51]
	v_pk_mul_f32 v[74:75], v[66:67], v[66:67]
	v_pk_mul_f32 v[76:77], v[64:65], v[64:65]
	s_mov_b64 s[0:1], 0x24000400
	s_waitcnt vmcnt(0) lgkmcnt(0)
	v_lshlrev_b32_e32 v48, 16, v100
	v_mul_f32_e32 v73, 0xbfb8aa3b, v48
	v_exp_f32_e32 v73, v73
	v_and_b32_e32 v49, 0xffff0000, v100
	v_add_f32_e32 v73, 1.0, v73
	v_rcp_f32_e32 v98, v73
	v_mul_f32_e32 v73, 0xbfb8aa3b, v49
	v_exp_f32_e32 v73, v73
	s_nop 0
	v_add_f32_e32 v73, 1.0, v73
	v_rcp_f32_e32 v99, v73
	s_nop 0
	v_pk_mul_f32 v[98:99], v[98:99], v[48:49]
	v_lshlrev_b32_e32 v48, 16, v101
	v_mul_f32_e32 v73, 0xbfb8aa3b, v48
	v_exp_f32_e32 v73, v73
	v_and_b32_e32 v49, 0xffff0000, v101
	v_add_f32_e32 v73, 1.0, v73
	v_rcp_f32_e32 v100, v73
	v_mul_f32_e32 v73, 0xbfb8aa3b, v49
	v_exp_f32_e32 v73, v73
	s_nop 0
	v_add_f32_e32 v73, 1.0, v73
	v_pk_fma_f32 v[52:53], v[52:53], v[72:73], v[112:113] op_sel_hi:[1,0,1] neg_lo:[0,0,1] neg_hi:[0,0,1]
	v_lshlrev_b32_e32 v112, 16, v162
	v_rcp_f32_e32 v101, v73
	v_pk_fma_f32 v[54:55], v[54:55], v[72:73], v[116:117] op_sel_hi:[1,0,1] neg_lo:[0,0,1] neg_hi:[0,0,1]
	v_mul_f32_e32 v73, 0xbfb8aa3b, v112
	v_exp_f32_e32 v73, v73
	v_and_b32_e32 v113, 0xffff0000, v162
	v_pk_mul_f32 v[156:157], v[52:53], v[52:53]
	v_pk_mul_f32 v[102:103], v[100:101], v[48:49]
	v_add_f32_e32 v73, 1.0, v73
	v_rcp_f32_e32 v116, v73
	v_mul_f32_e32 v73, 0xbfb8aa3b, v113
	v_exp_f32_e32 v73, v73
	v_lshl_add_u64 v[100:101], v[154:155], 0, v[192:193]
	v_pk_mul_f32 v[154:155], v[54:55], v[54:55]
	v_lshl_add_u64 v[48:49], v[100:101], 0, s[0:1]
	v_add_f32_e32 v73, 1.0, v73
	v_rcp_f32_e32 v117, v73
	s_mov_b32 s0, 0x800000
	v_pk_mul_f32 v[112:113], v[116:117], v[112:113]
	v_lshlrev_b32_e32 v116, 16, v163
	v_mul_f32_e32 v73, 0xbfb8aa3b, v116
	v_exp_f32_e32 v73, v73
	v_and_b32_e32 v117, 0xffff0000, v163
	v_add_f32_e32 v73, 1.0, v73
	v_rcp_f32_e32 v162, v73
	v_mul_f32_e32 v73, 0xbfb8aa3b, v117
	v_exp_f32_e32 v73, v73
	s_nop 0
	v_add_f32_e32 v73, 1.0, v73
	v_pk_fma_f32 v[56:57], v[56:57], v[72:73], v[118:119] op_sel_hi:[1,0,1] neg_lo:[0,0,1] neg_hi:[0,0,1]
	v_lshlrev_b32_e32 v118, 16, v146
	v_rcp_f32_e32 v163, v73
	v_pk_fma_f32 v[58:59], v[58:59], v[72:73], v[120:121] op_sel_hi:[1,0,1] neg_lo:[0,0,1] neg_hi:[0,0,1]
	v_mul_f32_e32 v73, 0xbfb8aa3b, v118
	v_exp_f32_e32 v73, v73
	v_and_b32_e32 v119, 0xffff0000, v146
	v_pk_mul_f32 v[166:167], v[56:57], v[56:57]
	v_pk_mul_f32 v[116:117], v[162:163], v[116:117]
	v_add_f32_e32 v73, 1.0, v73
	v_rcp_f32_e32 v120, v73
	v_mul_f32_e32 v73, 0xbfb8aa3b, v119
	v_exp_f32_e32 v73, v73
	v_pk_mul_f32 v[162:163], v[58:59], v[58:59]
	v_add_f32_e32 v73, 1.0, v73
	v_rcp_f32_e32 v121, v73
	s_nop 0
	v_pk_mul_f32 v[118:119], v[120:121], v[118:119]
	v_lshlrev_b32_e32 v120, 16, v147
	v_mul_f32_e32 v73, 0xbfb8aa3b, v120
	v_exp_f32_e32 v73, v73
	v_and_b32_e32 v121, 0xffff0000, v147
	v_add_f32_e32 v73, 1.0, v73
	v_rcp_f32_e32 v146, v73
	v_mul_f32_e32 v73, 0xbfb8aa3b, v121
	v_exp_f32_e32 v73, v73
	s_nop 0
	v_add_f32_e32 v73, 1.0, v73
	v_pk_fma_f32 v[60:61], v[60:61], v[72:73], v[122:123] op_sel_hi:[1,0,1] neg_lo:[0,0,1] neg_hi:[0,0,1]
	v_lshlrev_b32_e32 v122, 16, v136
	v_rcp_f32_e32 v147, v73
	v_pk_fma_f32 v[62:63], v[62:63], v[72:73], v[126:127] op_sel_hi:[1,0,1] neg_lo:[0,0,1] neg_hi:[0,0,1]
	v_mul_f32_e32 v73, 0xbfb8aa3b, v122
	v_exp_f32_e32 v73, v73
	v_and_b32_e32 v123, 0xffff0000, v136
	v_pk_mul_f32 v[120:121], v[146:147], v[120:121]
	v_pk_mul_f32 v[172:173], v[60:61], v[60:61]
	v_add_f32_e32 v73, 1.0, v73
	v_rcp_f32_e32 v126, v73
	v_mul_f32_e32 v73, 0xbfb8aa3b, v123
	v_exp_f32_e32 v73, v73
	v_pk_mul_f32 v[170:171], v[62:63], v[62:63]
	v_add_f32_e32 v73, 1.0, v73
	v_rcp_f32_e32 v127, v73
	s_nop 0
	v_pk_mul_f32 v[122:123], v[126:127], v[122:123]
	v_lshlrev_b32_e32 v126, 16, v137
	v_mul_f32_e32 v73, 0xbfb8aa3b, v126
	v_exp_f32_e32 v73, v73
	v_and_b32_e32 v127, 0xffff0000, v137
	v_add_f32_e32 v73, 1.0, v73
	v_rcp_f32_e32 v136, v73
	v_mul_f32_e32 v73, 0xbfb8aa3b, v127
	v_exp_f32_e32 v73, v73
	s_nop 0
	v_add_f32_e32 v73, 1.0, v73
	v_rcp_f32_e32 v137, v73
	v_pk_fma_f32 v[124:125], v[34:35], v[72:73], v[124:125] op_sel_hi:[1,0,1] neg_lo:[0,0,1] neg_hi:[0,0,1]
	v_pk_mul_f32 v[34:35], v[160:161], v[128:129]
	v_pk_mul_f32 v[176:177], v[124:125], v[124:125]
	v_pk_mul_f32 v[126:127], v[136:137], v[126:127]
	v_pk_fma_f32 v[136:137], v[32:33], v[72:73], v[34:35] op_sel_hi:[1,0,1] neg_lo:[0,0,1] neg_hi:[0,0,1]
	v_lshlrev_b32_e32 v32, 16, v182
	v_and_b32_e32 v33, 0xffff0000, v182
	v_mul_f32_e32 v34, 0xbfb8aa3b, v32
	v_mul_f32_e32 v35, 0xbfb8aa3b, v33
	v_exp_f32_e32 v34, v34
	v_exp_f32_e32 v35, v35
	v_pk_mul_f32 v[178:179], v[136:137], v[136:137]
	v_add_f32_e32 v34, 1.0, v34
	v_add_f32_e32 v35, 1.0, v35
	v_rcp_f32_e32 v34, v34
	v_rcp_f32_e32 v35, v35
	s_nop 0
	v_pk_mul_f32 v[146:147], v[34:35], v[32:33]
	v_lshlrev_b32_e32 v32, 16, v183
	v_and_b32_e32 v33, 0xffff0000, v183
	v_mul_f32_e32 v34, 0xbfb8aa3b, v32
	v_mul_f32_e32 v35, 0xbfb8aa3b, v33
	v_exp_f32_e32 v34, v34
	v_exp_f32_e32 v35, v35
	v_add_f32_e32 v34, 1.0, v34
	v_add_f32_e32 v35, 1.0, v35
	v_rcp_f32_e32 v34, v34
	v_rcp_f32_e32 v35, v35
	s_nop 0
	v_pk_mul_f32 v[128:129], v[34:35], v[32:33]
	v_pk_mul_f32 v[34:35], v[160:161], v[130:131]
	v_pk_mul_f32 v[32:33], v[160:161], v[138:139]
	v_pk_fma_f32 v[130:131], v[36:37], v[72:73], v[34:35] op_sel_hi:[1,0,1] neg_lo:[0,0,1] neg_hi:[0,0,1]
	v_lshlrev_b32_e32 v34, 16, v188
	v_and_b32_e32 v35, 0xffff0000, v188
	v_mul_f32_e32 v36, 0xbfb8aa3b, v34
	v_mul_f32_e32 v37, 0xbfb8aa3b, v35
	v_exp_f32_e32 v36, v36
	v_exp_f32_e32 v37, v37
	v_pk_fma_f32 v[32:33], v[38:39], v[72:73], v[32:33] op_sel_hi:[1,0,1] neg_lo:[0,0,1] neg_hi:[0,0,1]
	v_pk_mul_f32 v[184:185], v[130:131], v[130:131]
	v_add_f32_e32 v36, 1.0, v36
	v_add_f32_e32 v37, 1.0, v37
	v_rcp_f32_e32 v36, v36
	v_rcp_f32_e32 v37, v37
	v_pk_mul_f32 v[182:183], v[32:33], v[32:33]
	v_pk_mul_f32 v[138:139], v[36:37], v[34:35]
	v_lshlrev_b32_e32 v34, 16, v189
	v_and_b32_e32 v35, 0xffff0000, v189
	v_mul_f32_e32 v36, 0xbfb8aa3b, v34
	v_mul_f32_e32 v37, 0xbfb8aa3b, v35
	v_exp_f32_e32 v36, v36
	v_exp_f32_e32 v37, v37
	v_add_f32_e32 v36, 1.0, v36
	v_add_f32_e32 v37, 1.0, v37
	v_rcp_f32_e32 v36, v36
	v_rcp_f32_e32 v37, v37
	s_nop 0
	v_pk_mul_f32 v[38:39], v[36:37], v[34:35]
	v_pk_mul_f32 v[36:37], v[160:161], v[132:133]
	v_pk_mul_f32 v[34:35], v[160:161], v[144:145]
	v_pk_fma_f32 v[132:133], v[40:41], v[72:73], v[36:37] op_sel_hi:[1,0,1] neg_lo:[0,0,1] neg_hi:[0,0,1]
	v_lshlrev_b32_e32 v36, 16, v186
	v_and_b32_e32 v37, 0xffff0000, v186
	v_mul_f32_e32 v40, 0xbfb8aa3b, v36
	v_mul_f32_e32 v41, 0xbfb8aa3b, v37
	v_exp_f32_e32 v40, v40
	v_exp_f32_e32 v41, v41
	v_pk_fma_f32 v[34:35], v[42:43], v[72:73], v[34:35] op_sel_hi:[1,0,1] neg_lo:[0,0,1] neg_hi:[0,0,1]
	v_pk_mul_f32 v[42:43], v[160:161], v[148:149]
	v_add_f32_e32 v40, 1.0, v40
	v_add_f32_e32 v41, 1.0, v41
	v_rcp_f32_e32 v40, v40
	v_rcp_f32_e32 v41, v41
	v_pk_mul_f32 v[190:191], v[132:133], v[132:133]
	v_pk_mul_f32 v[188:189], v[34:35], v[34:35]
	v_pk_mul_f32 v[144:145], v[40:41], v[36:37]
	v_lshlrev_b32_e32 v36, 16, v187
	v_and_b32_e32 v37, 0xffff0000, v187
	v_mul_f32_e32 v40, 0xbfb8aa3b, v36
	v_mul_f32_e32 v41, 0xbfb8aa3b, v37
	v_exp_f32_e32 v40, v40
	v_exp_f32_e32 v41, v41
	v_add_f32_e32 v40, 1.0, v40
	v_add_f32_e32 v41, 1.0, v41
	v_rcp_f32_e32 v40, v40
	v_rcp_f32_e32 v41, v41
	s_nop 0
	v_pk_mul_f32 v[40:41], v[40:41], v[36:37]
	v_pk_mul_f32 v[36:37], v[160:161], v[164:165]
	s_nop 0
	v_pk_fma_f32 v[36:37], v[46:47], v[72:73], v[36:37] op_sel_hi:[1,0,1] neg_lo:[0,0,1] neg_hi:[0,0,1]
	v_pk_fma_f32 v[46:47], v[44:45], v[72:73], v[42:43] op_sel_hi:[1,0,1] neg_lo:[0,0,1] neg_hi:[0,0,1]
	v_lshlrev_b32_e32 v42, 16, v180
	v_and_b32_e32 v43, 0xffff0000, v180
	v_mul_f32_e32 v44, 0xbfb8aa3b, v42
	v_mul_f32_e32 v45, 0xbfb8aa3b, v43
	v_exp_f32_e32 v44, v44
	v_exp_f32_e32 v45, v45
	v_pk_mul_f32 v[186:187], v[46:47], v[46:47]
	v_pk_mul_f32 v[164:165], v[36:37], v[36:37]
	v_add_f32_e32 v44, 1.0, v44
	v_add_f32_e32 v45, 1.0, v45
	v_rcp_f32_e32 v44, v44
	v_rcp_f32_e32 v45, v45
	s_nop 0
	v_pk_mul_f32 v[148:149], v[44:45], v[42:43]
	v_lshlrev_b32_e32 v42, 16, v181
	v_and_b32_e32 v43, 0xffff0000, v181
	v_mul_f32_e32 v44, 0xbfb8aa3b, v42
	v_mul_f32_e32 v45, 0xbfb8aa3b, v43
	v_exp_f32_e32 v44, v44
	v_exp_f32_e32 v45, v45
	v_add_f32_e32 v44, 1.0, v44
	v_add_f32_e32 v45, 1.0, v45
	v_rcp_f32_e32 v44, v44
	v_rcp_f32_e32 v45, v45
	s_nop 0
	v_pk_mul_f32 v[42:43], v[44:45], v[42:43]
	v_pk_mul_f32 v[44:45], v[160:161], v[150:151]
	s_nop 0
	v_pk_fma_f32 v[18:19], v[18:19], v[72:73], v[44:45] op_sel_hi:[1,0,1] neg_lo:[0,0,1] neg_hi:[0,0,1]
	v_pk_mul_f32 v[44:45], v[160:161], v[140:141]
	v_pk_mul_f32 v[180:181], v[18:19], v[18:19]
	v_pk_fma_f32 v[140:141], v[16:17], v[72:73], v[44:45] op_sel_hi:[1,0,1] neg_lo:[0,0,1] neg_hi:[0,0,1]
	v_lshlrev_b32_e32 v16, 16, v174
	v_and_b32_e32 v17, 0xffff0000, v174
	v_mul_f32_e32 v44, 0xbfb8aa3b, v16
	v_mul_f32_e32 v45, 0xbfb8aa3b, v17
	v_exp_f32_e32 v44, v44
	v_exp_f32_e32 v45, v45
	v_pk_mul_f32 v[194:195], v[140:141], v[140:141]
	v_add_f32_e32 v44, 1.0, v44
	v_add_f32_e32 v45, 1.0, v45
	v_rcp_f32_e32 v44, v44
	v_rcp_f32_e32 v45, v45
	s_nop 0
	v_pk_mul_f32 v[150:151], v[44:45], v[16:17]
	v_lshlrev_b32_e32 v16, 16, v175
	v_and_b32_e32 v17, 0xffff0000, v175
	v_mul_f32_e32 v44, 0xbfb8aa3b, v16
	v_mul_f32_e32 v45, 0xbfb8aa3b, v17
	v_exp_f32_e32 v44, v44
	v_exp_f32_e32 v45, v45
	v_add_f32_e32 v44, 1.0, v44
	v_add_f32_e32 v45, 1.0, v45
	v_rcp_f32_e32 v44, v44
	v_rcp_f32_e32 v45, v45
	s_nop 0
	v_pk_mul_f32 v[44:45], v[44:45], v[16:17]
	v_pk_mul_f32 v[16:17], v[160:161], v[142:143]
	s_nop 0
	v_pk_fma_f32 v[16:17], v[22:23], v[72:73], v[16:17] op_sel_hi:[1,0,1] neg_lo:[0,0,1] neg_hi:[0,0,1]
	v_pk_mul_f32 v[22:23], v[160:161], v[134:135]
	v_pk_mul_f32 v[174:175], v[16:17], v[16:17]
	v_pk_fma_f32 v[134:135], v[20:21], v[72:73], v[22:23] op_sel_hi:[1,0,1] neg_lo:[0,0,1] neg_hi:[0,0,1]
	v_lshlrev_b32_e32 v20, 16, v168
	v_and_b32_e32 v21, 0xffff0000, v168
	v_mul_f32_e32 v22, 0xbfb8aa3b, v20
	v_mul_f32_e32 v23, 0xbfb8aa3b, v21
	v_exp_f32_e32 v22, v22
	v_exp_f32_e32 v23, v23
	v_pk_mul_f32 v[196:197], v[134:135], v[134:135]
	v_add_f32_e32 v22, 1.0, v22
	v_add_f32_e32 v23, 1.0, v23
	v_rcp_f32_e32 v22, v22
	v_rcp_f32_e32 v23, v23
	s_nop 0
	v_pk_mul_f32 v[142:143], v[22:23], v[20:21]
	v_lshlrev_b32_e32 v20, 16, v169
	v_and_b32_e32 v21, 0xffff0000, v169
	v_mul_f32_e32 v22, 0xbfb8aa3b, v20
	v_mul_f32_e32 v23, 0xbfb8aa3b, v21
	v_exp_f32_e32 v22, v22
	v_exp_f32_e32 v23, v23
	v_add_f32_e32 v22, 1.0, v22
	v_add_f32_e32 v23, 1.0, v23
	v_rcp_f32_e32 v22, v22
	v_rcp_f32_e32 v23, v23
	s_nop 0
	v_pk_mul_f32 v[22:23], v[22:23], v[20:21]
	v_pk_mul_f32 v[20:21], v[160:161], v[106:107]
	s_nop 0
	v_pk_fma_f32 v[20:21], v[26:27], v[72:73], v[20:21] op_sel_hi:[1,0,1] neg_lo:[0,0,1] neg_hi:[0,0,1]
	v_pk_mul_f32 v[26:27], v[160:161], v[104:105]
	v_pk_mul_f32 v[168:169], v[20:21], v[20:21]
	v_pk_fma_f32 v[104:105], v[24:25], v[72:73], v[26:27] op_sel_hi:[1,0,1] neg_lo:[0,0,1] neg_hi:[0,0,1]
	v_lshlrev_b32_e32 v24, 16, v158
	v_and_b32_e32 v25, 0xffff0000, v158
	v_mul_f32_e32 v26, 0xbfb8aa3b, v24
	v_mul_f32_e32 v27, 0xbfb8aa3b, v25
	v_exp_f32_e32 v26, v26
	v_exp_f32_e32 v27, v27
	v_pk_mul_f32 v[198:199], v[104:105], v[104:105]
	v_add_f32_e32 v26, 1.0, v26
	v_add_f32_e32 v27, 1.0, v27
	v_rcp_f32_e32 v26, v26
	v_rcp_f32_e32 v27, v27
	s_nop 0
	v_pk_mul_f32 v[106:107], v[26:27], v[24:25]
	v_lshlrev_b32_e32 v24, 16, v159
	v_and_b32_e32 v25, 0xffff0000, v159
	v_mul_f32_e32 v26, 0xbfb8aa3b, v24
	v_mul_f32_e32 v27, 0xbfb8aa3b, v25
	v_exp_f32_e32 v26, v26
	v_exp_f32_e32 v27, v27
	v_add_f32_e32 v26, 1.0, v26
	v_add_f32_e32 v27, 1.0, v27
	v_rcp_f32_e32 v26, v26
	v_rcp_f32_e32 v27, v27
	s_nop 0
	v_pk_mul_f32 v[26:27], v[26:27], v[24:25]
	v_pk_mul_f32 v[24:25], v[160:161], v[92:93]
	s_nop 0
	v_pk_fma_f32 v[24:25], v[30:31], v[72:73], v[24:25] op_sel_hi:[1,0,1] neg_lo:[0,0,1] neg_hi:[0,0,1]
	v_pk_mul_f32 v[30:31], v[160:161], v[90:91]
	v_pk_mul_f32 v[158:159], v[24:25], v[24:25]
	v_pk_fma_f32 v[90:91], v[28:29], v[72:73], v[30:31] op_sel_hi:[1,0,1] neg_lo:[0,0,1] neg_hi:[0,0,1]
	v_lshlrev_b32_e32 v28, 16, v152
	v_and_b32_e32 v29, 0xffff0000, v152
	v_mul_f32_e32 v30, 0xbfb8aa3b, v28
	v_mul_f32_e32 v31, 0xbfb8aa3b, v29
	v_exp_f32_e32 v30, v30
	v_exp_f32_e32 v31, v31
	v_pk_mul_f32 v[200:201], v[90:91], v[90:91]
	v_add_f32_e32 v30, 1.0, v30
	v_add_f32_e32 v31, 1.0, v31
	v_rcp_f32_e32 v30, v30
	v_rcp_f32_e32 v31, v31
	s_nop 0
	v_pk_mul_f32 v[92:93], v[30:31], v[28:29]
	v_lshlrev_b32_e32 v28, 16, v153
	v_and_b32_e32 v29, 0xffff0000, v153
	v_mul_f32_e32 v30, 0xbfb8aa3b, v28
	v_mul_f32_e32 v31, 0xbfb8aa3b, v29
	v_exp_f32_e32 v30, v30
	v_exp_f32_e32 v31, v31
	v_add_f32_e32 v30, 1.0, v30
	v_add_f32_e32 v31, 1.0, v31
	v_rcp_f32_e32 v30, v30
	v_rcp_f32_e32 v31, v31
	s_nop 0
	v_pk_mul_f32 v[28:29], v[30:31], v[28:29]
	v_pk_mul_f32 v[30:31], v[160:161], v[88:89]
	s_nop 0
	v_pk_fma_f32 v[2:3], v[2:3], v[72:73], v[30:31] op_sel_hi:[1,0,1] neg_lo:[0,0,1] neg_hi:[0,0,1]
	v_pk_mul_f32 v[30:31], v[160:161], v[86:87]
	v_pk_mul_f32 v[152:153], v[2:3], v[2:3]
	v_pk_fma_f32 v[86:87], v[0:1], v[72:73], v[30:31] op_sel_hi:[1,0,1] neg_lo:[0,0,1] neg_hi:[0,0,1]
	v_lshlrev_b32_e32 v0, 16, v114
	v_and_b32_e32 v1, 0xffff0000, v114
	v_mul_f32_e32 v30, 0xbfb8aa3b, v0
	v_mul_f32_e32 v31, 0xbfb8aa3b, v1
	v_exp_f32_e32 v30, v30
	v_exp_f32_e32 v31, v31
	v_pk_mul_f32 v[202:203], v[86:87], v[86:87]
	v_add_f32_e32 v30, 1.0, v30
	v_add_f32_e32 v31, 1.0, v31
	v_rcp_f32_e32 v30, v30
	v_rcp_f32_e32 v31, v31
	s_nop 0
	v_pk_mul_f32 v[88:89], v[30:31], v[0:1]
	v_lshlrev_b32_e32 v0, 16, v115
	v_and_b32_e32 v1, 0xffff0000, v115
	v_mul_f32_e32 v30, 0xbfb8aa3b, v0
	v_mul_f32_e32 v31, 0xbfb8aa3b, v1
	v_exp_f32_e32 v30, v30
	v_exp_f32_e32 v31, v31
	v_add_f32_e32 v30, 1.0, v30
	v_add_f32_e32 v31, 1.0, v31
	v_rcp_f32_e32 v30, v30
	v_rcp_f32_e32 v31, v31
	s_nop 0
	v_pk_mul_f32 v[30:31], v[30:31], v[0:1]
	v_pk_mul_f32 v[0:1], v[160:161], v[84:85]
	s_nop 0
	v_pk_fma_f32 v[0:1], v[6:7], v[72:73], v[0:1] op_sel_hi:[1,0,1] neg_lo:[0,0,1] neg_hi:[0,0,1]
	v_pk_mul_f32 v[6:7], v[160:161], v[82:83]
	v_pk_mul_f32 v[84:85], v[0:1], v[0:1]
	v_pk_fma_f32 v[6:7], v[4:5], v[72:73], v[6:7] op_sel_hi:[1,0,1] neg_lo:[0,0,1] neg_hi:[0,0,1]
	v_lshlrev_b32_e32 v4, 16, v94
	v_mul_f32_e32 v73, 0xbfb8aa3b, v4
	v_exp_f32_e32 v73, v73
	v_and_b32_e32 v5, 0xffff0000, v94
	v_pk_mul_f32 v[114:115], v[6:7], v[6:7]
	v_add_f32_e32 v73, 1.0, v73
	v_rcp_f32_e32 v82, v73
	v_mul_f32_e32 v73, 0xbfb8aa3b, v5
	v_exp_f32_e32 v73, v73
	s_nop 0
	v_add_f32_e32 v73, 1.0, v73
	v_rcp_f32_e32 v83, v73
	s_nop 0
	v_pk_mul_f32 v[82:83], v[82:83], v[4:5]
	v_lshlrev_b32_e32 v4, 16, v95
	v_mul_f32_e32 v73, 0xbfb8aa3b, v4
	v_exp_f32_e32 v73, v73
	v_and_b32_e32 v5, 0xffff0000, v95
	v_add_f32_e32 v73, 1.0, v73
	v_rcp_f32_e32 v94, v73
	v_mul_f32_e32 v73, 0xbfb8aa3b, v5
	v_exp_f32_e32 v73, v73
	s_nop 0
	v_add_f32_e32 v73, 1.0, v73
	v_rcp_f32_e32 v95, v73
	v_pk_fma_f32 v[10:11], v[10:11], v[72:73], v[80:81] op_sel_hi:[1,0,1] neg_lo:[0,0,1] neg_hi:[0,0,1]
	v_pk_fma_f32 v[72:73], v[8:9], v[72:73], v[78:79] op_sel_hi:[1,0,1] neg_lo:[0,0,1] neg_hi:[0,0,1]
	v_lshlrev_b32_e32 v78, 16, v70
	v_and_b32_e32 v79, 0xffff0000, v70
	v_mul_f32_e32 v70, 0xbfb8aa3b, v78
	v_exp_f32_e32 v70, v70
	v_pk_mul_f32 v[4:5], v[94:95], v[4:5]
	v_pk_mul_f32 v[8:9], v[72:73], v[72:73]
	v_pk_mul_f32 v[80:81], v[10:11], v[10:11]
	v_add_f32_e32 v70, 1.0, v70
	v_rcp_f32_e32 v94, v70
	v_mul_f32_e32 v70, 0xbfb8aa3b, v79
	v_exp_f32_e32 v70, v70
	s_nop 0
	v_add_f32_e32 v70, 1.0, v70
	v_rcp_f32_e32 v95, v70
	v_add_f32_e32 v70, v110, v111
	v_add_f32_e32 v70, v70, v108
	v_add_f32_e32 v70, v70, v109
	v_add_f32_e32 v70, v70, v156
	v_add_f32_e32 v70, v70, v157
	v_add_f32_e32 v70, v70, v154
	v_add_f32_e32 v70, v70, v155
	v_add_f32_e32 v70, v70, v166
	v_add_f32_e32 v70, v70, v167
	v_add_f32_e32 v70, v70, v162
	v_add_f32_e32 v70, v70, v163
	v_add_f32_e32 v70, v70, v172
	v_add_f32_e32 v70, v70, v173
	v_add_f32_e32 v70, v70, v170
	v_add_f32_e32 v70, v70, v171
	v_add_f32_e32 v70, v70, v178
	v_add_f32_e32 v70, v70, v179
	v_add_f32_e32 v70, v70, v176
	v_add_f32_e32 v70, v70, v177
	v_add_f32_e32 v70, v70, v184
	v_add_f32_e32 v70, v70, v185
	v_add_f32_e32 v70, v70, v182
	v_add_f32_e32 v70, v70, v183
	v_add_f32_e32 v70, v70, v190
	v_add_f32_e32 v70, v70, v191
	v_add_f32_e32 v70, v70, v188
	v_add_f32_e32 v70, v70, v189
	v_add_f32_e32 v70, v70, v186
	v_add_f32_e32 v70, v70, v187
	v_add_f32_e32 v70, v70, v164
	v_add_f32_e32 v70, v70, v165
	v_add_f32_e32 v70, v70, v194
	v_add_f32_e32 v70, v70, v195
	v_add_f32_e32 v70, v70, v180
	v_add_f32_e32 v70, v70, v181
	v_add_f32_e32 v70, v70, v196
	v_add_f32_e32 v70, v70, v197
	v_add_f32_e32 v70, v70, v174
	v_add_f32_e32 v70, v70, v175
	v_add_f32_e32 v70, v70, v198
	v_add_f32_e32 v70, v70, v199
	v_add_f32_e32 v70, v70, v168
	v_add_f32_e32 v70, v70, v169
	v_add_f32_e32 v70, v70, v200
	v_add_f32_e32 v70, v70, v201
	v_add_f32_e32 v70, v70, v158
	v_add_f32_e32 v70, v70, v159
	v_add_f32_e32 v70, v70, v202
	v_add_f32_e32 v70, v70, v203
	v_add_f32_e32 v70, v70, v152
	v_add_f32_e32 v70, v70, v153
	v_add_f32_e32 v70, v70, v114
	v_add_f32_e32 v70, v70, v115
	v_add_f32_e32 v70, v70, v84
	v_add_f32_e32 v70, v70, v85
	v_add_f32_e32 v8, v70, v8
	v_add_f32_e32 v8, v8, v9
	v_add_f32_e32 v8, v8, v80
	v_add_f32_e32 v8, v8, v81
	v_add_f32_e32 v8, v8, v74
	v_add_f32_e32 v8, v8, v75
	v_add_f32_e32 v8, v8, v76
	v_add_f32_e32 v8, v8, v77
	ds_bpermute_b32 v9, v218, v8
	v_pk_mul_f32 v[78:79], v[94:95], v[78:79]
	s_waitcnt lgkmcnt(0)
	v_add_f32_e32 v8, v8, v9
	v_fmamk_f32 v8, v8, 0x3c000000, v207
	v_cmp_gt_f32_e32 vcc, s0, v8
	v_mul_f32_e32 v9, 0x4b800000, v8
	s_brev_b32 s0, 36
	v_cndmask_b32_e32 v8, v8, v9, vcc
	v_rsq_f32_e32 v8, v8
	s_nop 0
	v_mul_f32_e32 v9, 0x45800000, v8
	v_cndmask_b32_e32 v8, v8, v9, vcc
	v_mul_f32_e32 v8, v204, v8
	v_pk_mul_f32 v[74:75], v[96:97], v[8:9] op_sel_hi:[1,0]
	v_pk_mul_f32 v[50:51], v[50:51], v[8:9] op_sel_hi:[1,0]
	v_pk_mul_f32 v[12:13], v[74:75], v[12:13]
	v_pk_mul_f32 v[14:15], v[50:51], v[14:15]
	v_pk_mul_f32 v[12:13], v[98:99], v[12:13]
	v_pk_mul_f32 v[14:15], v[102:103], v[14:15]
	v_cvt_pk_bf16_f32 v232, v12, v13
	v_cvt_pk_bf16_f32 v233, v14, v15
	v_add_co_u32_e32 v14, vcc, s0, v100
	v_pk_mul_f32 v[50:51], v[52:53], v[8:9] op_sel_hi:[1,0]
	s_nop 0
	v_addc_co_u32_e32 v15, vcc, 0, v101, vcc
	global_load_dwordx4 v[252:255], v205, s[10:11] offset:128
	v_pk_mul_f32 v[32:33], v[32:33], v[8:9] op_sel_hi:[1,0]
	v_pk_mul_f32 v[18:19], v[18:19], v[8:9] op_sel_hi:[1,0]
	v_pk_mul_f32 v[16:17], v[16:17], v[8:9] op_sel_hi:[1,0]
	v_pk_mul_f32 v[2:3], v[2:3], v[8:9] op_sel_hi:[1,0]
	v_pk_mul_f32 v[0:1], v[0:1], v[8:9] op_sel_hi:[1,0]
	v_pk_mul_f32 v[10:11], v[10:11], v[8:9] op_sel_hi:[1,0]
	v_pk_mul_f32 v[12:13], v[50:51], v[240:241]
	v_pk_mul_f32 v[50:51], v[54:55], v[8:9] op_sel_hi:[1,0]
	v_pk_mul_f32 v[12:13], v[112:113], v[12:13]
	v_pk_mul_f32 v[14:15], v[50:51], v[242:243]
	v_cvt_pk_bf16_f32 v234, v12, v13
	v_pk_mul_f32 v[14:15], v[116:117], v[14:15]
	v_pk_mul_f32 v[50:51], v[56:57], v[8:9] op_sel_hi:[1,0]
	v_cvt_pk_bf16_f32 v235, v14, v15
	v_and_b32_e32 v236, 32, v209
	v_lshrrev_b32_e32 v236, 2, v236
	v_mov_b32_e32 v237, 0
	v_lshl_add_u64 v[236:237], v[48:49], 0, v[236:237]
	s_nop 1
	v_permlane32_swap_b32_e32 v232, v234
	v_permlane32_swap_b32_e32 v233, v235
	flat_store_dwordx4 v[236:237], v[232:235] offset:0
	global_load_dwordx4 v[240:243], v205, s[10:11] offset:160
	v_pk_mul_f32 v[12:13], v[50:51], v[244:245]
	v_pk_mul_f32 v[50:51], v[58:59], v[8:9] op_sel_hi:[1,0]
	v_pk_mul_f32 v[12:13], v[118:119], v[12:13]
	v_pk_mul_f32 v[14:15], v[50:51], v[246:247]
	v_cvt_pk_bf16_f32 v232, v12, v13
	v_pk_mul_f32 v[14:15], v[120:121], v[14:15]
	v_pk_mul_f32 v[50:51], v[60:61], v[8:9] op_sel_hi:[1,0]
	v_cvt_pk_bf16_f32 v233, v14, v15
	global_load_dwordx4 v[244:247], v205, s[10:11] offset:192
	v_pk_mul_f32 v[12:13], v[50:51], v[248:249]
	v_pk_mul_f32 v[50:51], v[62:63], v[8:9] op_sel_hi:[1,0]
	v_pk_mul_f32 v[12:13], v[122:123], v[12:13]
	v_pk_mul_f32 v[14:15], v[50:51], v[250:251]
	v_cvt_pk_bf16_f32 v234, v12, v13
	v_pk_mul_f32 v[14:15], v[126:127], v[14:15]
	v_pk_mul_f32 v[50:51], v[136:137], v[8:9] op_sel_hi:[1,0]
	v_cvt_pk_bf16_f32 v235, v14, v15
	s_nop 1
	v_permlane32_swap_b32_e32 v232, v234
	v_permlane32_swap_b32_e32 v233, v235
	flat_store_dwordx4 v[236:237], v[232:235] offset:32
	global_load_dwordx4 v[248:251], v205, s[10:11] offset:224
	s_waitcnt vmcnt(5)
	v_pk_mul_f32 v[12:13], v[50:51], v[252:253]
	v_pk_mul_f32 v[50:51], v[124:125], v[8:9] op_sel_hi:[1,0]
	v_pk_mul_f32 v[12:13], v[146:147], v[12:13]
	v_pk_mul_f32 v[14:15], v[50:51], v[254:255]
	v_cvt_pk_bf16_f32 v232, v12, v13
	v_pk_mul_f32 v[14:15], v[128:129], v[14:15]
	v_pk_mul_f32 v[50:51], v[130:131], v[8:9] op_sel_hi:[1,0]
	v_cvt_pk_bf16_f32 v233, v14, v15
	global_load_dwordx4 v[252:255], v205, s[10:11] offset:256
	s_waitcnt vmcnt(4)
	v_pk_mul_f32 v[12:13], v[50:51], v[240:241]
	v_pk_mul_f32 v[14:15], v[32:33], v[242:243]
	v_pk_mul_f32 v[12:13], v[138:139], v[12:13]
	v_pk_mul_f32 v[14:15], v[38:39], v[14:15]
	v_cvt_pk_bf16_f32 v234, v12, v13
	v_cvt_pk_bf16_f32 v235, v14, v15
	s_nop 1
	v_permlane32_swap_b32_e32 v232, v234
	v_permlane32_swap_b32_e32 v233, v235
	flat_store_dwordx4 v[236:237], v[232:235] offset:64
	global_load_dwordx4 v[240:243], v205, s[10:11] offset:288
	v_pk_mul_f32 v[32:33], v[132:133], v[8:9] op_sel_hi:[1,0]
	s_waitcnt vmcnt(5)
	v_pk_mul_f32 v[12:13], v[32:33], v[244:245]
	v_pk_mul_f32 v[32:33], v[34:35], v[8:9] op_sel_hi:[1,0]
	v_pk_mul_f32 v[12:13], v[144:145], v[12:13]
	v_pk_mul_f32 v[14:15], v[32:33], v[246:247]
	v_cvt_pk_bf16_f32 v232, v12, v13
	v_pk_mul_f32 v[14:15], v[40:41], v[14:15]
	v_pk_mul_f32 v[32:33], v[46:47], v[8:9] op_sel_hi:[1,0]
	v_cvt_pk_bf16_f32 v233, v14, v15
	global_load_dwordx4 v[244:247], v205, s[10:11] offset:320
	s_waitcnt vmcnt(4)
	v_pk_mul_f32 v[12:13], v[32:33], v[248:249]
	v_pk_mul_f32 v[32:33], v[36:37], v[8:9] op_sel_hi:[1,0]
	v_pk_mul_f32 v[12:13], v[148:149], v[12:13]
	v_pk_mul_f32 v[14:15], v[32:33], v[250:251]
	v_cvt_pk_bf16_f32 v234, v12, v13
	v_pk_mul_f32 v[14:15], v[42:43], v[14:15]
	v_pk_mul_f32 v[32:33], v[140:141], v[8:9] op_sel_hi:[1,0]
	v_cvt_pk_bf16_f32 v235, v14, v15
	s_nop 1
	v_permlane32_swap_b32_e32 v232, v234
	v_permlane32_swap_b32_e32 v233, v235
	flat_store_dwordx4 v[236:237], v[232:235] offset:96
	global_load_dwordx4 v[248:251], v205, s[10:11] offset:352
	s_waitcnt vmcnt(5)
	v_pk_mul_f32 v[12:13], v[32:33], v[252:253]
	v_pk_mul_f32 v[14:15], v[18:19], v[254:255]
	v_pk_mul_f32 v[12:13], v[150:151], v[12:13]
	v_pk_mul_f32 v[14:15], v[44:45], v[14:15]
	v_cvt_pk_bf16_f32 v232, v12, v13
	v_cvt_pk_bf16_f32 v233, v14, v15
	global_load_dwordx4 v[252:255], v205, s[10:11] offset:384
	v_pk_mul_f32 v[18:19], v[134:135], v[8:9] op_sel_hi:[1,0]
	s_waitcnt vmcnt(4)
	v_pk_mul_f32 v[14:15], v[16:17], v[242:243]
	v_pk_mul_f32 v[12:13], v[18:19], v[240:241]
	v_pk_mul_f32 v[14:15], v[22:23], v[14:15]
	v_pk_mul_f32 v[12:13], v[142:143], v[12:13]
	v_pk_mul_f32 v[16:17], v[104:105], v[8:9] op_sel_hi:[1,0]
	v_cvt_pk_bf16_f32 v234, v12, v13
	v_cvt_pk_bf16_f32 v235, v14, v15
	s_nop 1
	v_permlane32_swap_b32_e32 v232, v234
	v_permlane32_swap_b32_e32 v233, v235
	flat_store_dwordx4 v[236:237], v[232:235] offset:128
	global_load_dwordx4 v[240:243], v205, s[10:11] offset:416
	s_waitcnt vmcnt(5)
	v_pk_mul_f32 v[12:13], v[16:17], v[244:245]
	v_pk_mul_f32 v[16:17], v[20:21], v[8:9] op_sel_hi:[1,0]
	v_pk_mul_f32 v[12:13], v[106:107], v[12:13]
	v_pk_mul_f32 v[14:15], v[16:17], v[246:247]
	v_cvt_pk_bf16_f32 v232, v12, v13
	v_pk_mul_f32 v[14:15], v[26:27], v[14:15]
	v_pk_mul_f32 v[16:17], v[90:91], v[8:9] op_sel_hi:[1,0]
	v_cvt_pk_bf16_f32 v233, v14, v15
	global_load_dwordx4 v[244:247], v205, s[10:11] offset:448
	s_waitcnt vmcnt(4)
	v_pk_mul_f32 v[12:13], v[16:17], v[248:249]
	v_pk_mul_f32 v[16:17], v[24:25], v[8:9] op_sel_hi:[1,0]
	v_pk_mul_f32 v[12:13], v[92:93], v[12:13]
	v_pk_mul_f32 v[14:15], v[16:17], v[250:251]
	v_cvt_pk_bf16_f32 v234, v12, v13
	v_pk_mul_f32 v[14:15], v[28:29], v[14:15]
	v_pk_mul_f32 v[16:17], v[86:87], v[8:9] op_sel_hi:[1,0]
	v_cvt_pk_bf16_f32 v235, v14, v15
	s_nop 1
	v_permlane32_swap_b32_e32 v232, v234
	v_permlane32_swap_b32_e32 v233, v235
	flat_store_dwordx4 v[236:237], v[232:235] offset:160
	global_load_dwordx4 v[248:251], v205, s[10:11] offset:480
	s_waitcnt vmcnt(5)
	v_pk_mul_f32 v[12:13], v[16:17], v[252:253]
	v_pk_mul_f32 v[2:3], v[2:3], v[254:255]
	v_pk_mul_f32 v[12:13], v[88:89], v[12:13]
	v_pk_mul_f32 v[2:3], v[30:31], v[2:3]
	v_cvt_pk_bf16_f32 v232, v12, v13
	v_cvt_pk_bf16_f32 v233, v2, v3
	v_pk_mul_f32 v[2:3], v[6:7], v[8:9] op_sel_hi:[1,0]
	s_waitcnt vmcnt(3)
	v_pk_mul_f32 v[0:1], v[0:1], v[242:243]
	v_pk_mul_f32 v[2:3], v[2:3], v[240:241]
	v_pk_mul_f32 v[0:1], v[4:5], v[0:1]
	v_pk_mul_f32 v[2:3], v[82:83], v[2:3]
	v_pk_mul_f32 v[4:5], v[72:73], v[8:9] op_sel_hi:[1,0]
	v_cvt_pk_bf16_f32 v234, v2, v3
	v_cvt_pk_bf16_f32 v235, v0, v1
	s_nop 1
	v_permlane32_swap_b32_e32 v232, v234
	v_permlane32_swap_b32_e32 v233, v235
	flat_store_dwordx4 v[236:237], v[232:235] offset:192
	s_waitcnt vmcnt(3)
	v_pk_mul_f32 v[0:1], v[4:5], v[244:245]
	s_nop 0
	v_pk_mul_f32 v[0:1], v[78:79], v[0:1]
	v_lshlrev_b32_e32 v4, 16, v71
	v_cvt_pk_bf16_f32 v232, v0, v1
	v_mul_f32_e32 v1, 0xbfb8aa3b, v4
	v_exp_f32_e32 v1, v1
	v_and_b32_e32 v5, 0xffff0000, v71
	v_pk_mul_f32 v[2:3], v[10:11], v[246:247]
	v_pk_mul_f32 v[10:11], v[66:67], v[8:9] op_sel_hi:[1,0]
	v_add_f32_e32 v1, 1.0, v1
	v_rcp_f32_e32 v6, v1
	v_mul_f32_e32 v1, 0xbfb8aa3b, v5
	v_exp_f32_e32 v1, v1
	v_pk_mul_f32 v[8:9], v[64:65], v[8:9] op_sel_hi:[1,0]
	v_add_f32_e32 v1, 1.0, v1
	v_rcp_f32_e32 v7, v1
	s_nop 0
	v_pk_mul_f32 v[4:5], v[6:7], v[4:5]
	s_nop 0
	v_pk_mul_f32 v[2:3], v[4:5], v[2:3]
	v_lshlrev_b32_e32 v4, 16, v68
	v_cvt_pk_bf16_f32 v233, v2, v3
	v_and_b32_e32 v5, 0xffff0000, v68
	v_mul_f32_e32 v6, 0xbfb8aa3b, v4
	v_mul_f32_e32 v7, 0xbfb8aa3b, v5
	v_exp_f32_e32 v6, v6
	v_exp_f32_e32 v7, v7
	v_add_f32_e32 v6, 1.0, v6
	v_add_f32_e32 v7, 1.0, v7
	v_rcp_f32_e32 v6, v6
	v_rcp_f32_e32 v7, v7
	s_waitcnt vmcnt(1)
	v_pk_mul_f32 v[0:1], v[10:11], v[248:249]
	v_pk_mul_f32 v[4:5], v[6:7], v[4:5]
	v_pk_mul_f32 v[2:3], v[8:9], v[250:251]
	v_pk_mul_f32 v[0:1], v[4:5], v[0:1]
	v_lshlrev_b32_e32 v4, 16, v69
	v_cvt_pk_bf16_f32 v234, v0, v1
	v_mul_f32_e32 v1, 0xbfb8aa3b, v4
	v_exp_f32_e32 v1, v1
	v_and_b32_e32 v5, 0xffff0000, v69
	v_add_f32_e32 v1, 1.0, v1
	v_rcp_f32_e32 v6, v1
	v_mul_f32_e32 v1, 0xbfb8aa3b, v5
	v_exp_f32_e32 v1, v1
	s_nop 0
	v_add_f32_e32 v1, 1.0, v1
	v_rcp_f32_e32 v7, v1
	s_nop 0
	v_pk_mul_f32 v[4:5], v[6:7], v[4:5]
	s_nop 0
	v_pk_mul_f32 v[2:3], v[4:5], v[2:3]
	s_nop 0
	v_cvt_pk_bf16_f32 v235, v2, v3
	s_nop 1
	v_permlane32_swap_b32_e32 v232, v234
	v_permlane32_swap_b32_e32 v233, v235
	flat_store_dwordx4 v[236:237], v[232:235] offset:224
	s_branch .LBB0_924
